# v27 + split-K sample-row tiles raise to priority 2 (one above the partner block's residual tile) in their MFMA sections
# baseline (speedup 1.0000x reference)
;     ...
;   __syncthreads();
;   G2_STAGE(0); G2_STAGE(1);
;   const int fsw = (0x78 >> (((r16 >> 2) & 3) * 2)) & 3;
;   const int aoff = (wm * 128 + r16) * 64 + ((quad ^ fsw) << 4);
;   const int boff = 16384 + (wn * 64 + r16) * 64 + ((quad ^ fsw) << 4);
;   for (int kt = 0; kt < nk; kt++) {
;     if (kt + 1 < nk) asm volatile("s_waitcnt vmcnt(6)" ::: "memory");
;     else asm volatile("s_waitcnt vmcnt(0)" ::: "memory");
;     __builtin_amdgcn_s_barrier();
;     asm volatile("" ::: "memory");
;     if (kt + 2 < nk) G2_STAGE(kt + 2);
;     const char* cS = smem + (kt % 3) * 24576;
;     bf16x8 xa[8], wb[4];
; #pragma unroll
;     for (int f = 0; f < 8; f++) xa[f] = *(const bf16x8*)(cS + aoff + f * 1024);
; #pragma unroll
;     for (int f = 0; f < 4; f++) wb[f] = *(const bf16x8*)(cS + boff + f * 1024);
; #pragma unroll
;     for (int nf = 0; nf < 4; nf++)
; #pragma unroll
;       for (int mf = 0; mf < 8; mf++)
;         acc[nf][mf] = __builtin_amdgcn_mfma_f32_16x16x32_bf16(wb[nf], xa[mf], acc[nf][mf], 0, 0, 0);
;   }
.Lta11_loop:
	.p2align 3
	s_waitcnt vmcnt(6) lgkmcnt(0)
	s_barrier
	s_setprio 2
	v_add_u32_e32 v144, s40, v136
	v_mfma_f32_16x16x32_bf16 v[126:129], v[184:187], v[146:149], v[126:129]
	ds_read_b128 v[200:203], v144 offset:0
	v_mfma_f32_16x16x32_bf16 v[122:125], v[184:187], v[152:155], v[122:125]
	ds_read_b128 v[204:207], v144 offset:1024
	v_mfma_f32_16x16x32_bf16 v[118:121], v[184:187], v[156:159], v[118:121]
	ds_read_b128 v[208:211], v144 offset:2048
	v_mfma_f32_16x16x32_bf16 v[114:117], v[184:187], v[162:165], v[114:117]
	ds_read_b128 v[212:215], v144 offset:3072
	v_mfma_f32_16x16x32_bf16 v[110:113], v[184:187], v[166:169], v[110:113]
	ds_read_b128 v[216:219], v144 offset:4096
	v_mfma_f32_16x16x32_bf16 v[106:109], v[184:187], v[170:173], v[106:109]
	ds_read_b128 v[220:223], v144 offset:5120
	v_mfma_f32_16x16x32_bf16 v[102:105], v[184:187], v[176:179], v[102:105]
	ds_read_b128 v[224:227], v144 offset:6144
	v_mfma_f32_16x16x32_bf16 v[98:101], v[184:187], v[180:183], v[98:101]
	ds_read_b128 v[228:231], v144 offset:7168
	v_mfma_f32_16x16x32_bf16 v[94:97], v[188:191], v[146:149], v[94:97]
	v_add_u32_e64 v144, s40, v137
	v_mfma_f32_16x16x32_bf16 v[90:93], v[188:191], v[152:155], v[90:93]
	v_mfma_f32_16x16x32_bf16 v[86:89], v[188:191], v[156:159], v[86:89]
	ds_read_b128 v[232:235], v144 offset:16384
	v_mfma_f32_16x16x32_bf16 v[82:85], v[188:191], v[162:165], v[82:85]
	ds_read_b128 v[236:239], v144 offset:17408
	v_mfma_f32_16x16x32_bf16 v[78:81], v[188:191], v[166:169], v[78:81]
	ds_read_b128 v[240:243], v144 offset:18432
	v_mfma_f32_16x16x32_bf16 v[74:77], v[188:191], v[170:173], v[74:77]
	ds_read_b128 v[244:247], v144 offset:19456
	v_mfma_f32_16x16x32_bf16 v[70:73], v[188:191], v[176:179], v[70:73]
	s_add_i32 s42, s46, s41
	s_mov_b32 m0, s42
	v_lshl_add_u64 v[142:143], v[132:133], 0, s[2:3]
	v_mfma_f32_16x16x32_bf16 v[66:69], v[188:191], v[180:183], v[66:69]
	global_load_lds_dwordx4 v[132:133], off
	s_add_i32 m0, m0, 0x1000
	v_mfma_f32_16x16x32_bf16 v[62:65], v[192:195], v[146:149], v[62:65]
	v_mfma_f32_16x16x32_bf16 v[58:61], v[192:195], v[152:155], v[58:61]
	v_mfma_f32_16x16x32_bf16 v[54:57], v[192:195], v[156:159], v[54:57]
	global_load_lds_dwordx4 v[142:143], off
	v_lshl_add_u64 v[142:143], v[142:143], 0, s[2:3]
	s_add_i32 m0, m0, 0x1000
	v_mfma_f32_16x16x32_bf16 v[50:53], v[192:195], v[162:165], v[50:53]
	v_mfma_f32_16x16x32_bf16 v[46:49], v[192:195], v[166:169], v[46:49]
	v_mfma_f32_16x16x32_bf16 v[42:45], v[192:195], v[170:173], v[42:45]
	global_load_lds_dwordx4 v[142:143], off
	v_lshl_add_u64 v[142:143], v[142:143], 0, s[2:3]
	s_add_i32 m0, m0, 0x1000
	v_mfma_f32_16x16x32_bf16 v[38:41], v[192:195], v[176:179], v[38:41]
	v_mfma_f32_16x16x32_bf16 v[34:37], v[192:195], v[180:183], v[34:37]
	s_setprio 0
	s_nop 0
	v_mfma_f32_16x16x32_bf16 v[30:33], v[196:199], v[146:149], v[30:33]
	global_load_lds_dwordx4 v[142:143], off
	s_add_i32 m0, m0, 0x1000
	v_lshl_add_u64 v[142:143], v[134:135], 0, s[2:3]
	v_mfma_f32_16x16x32_bf16 v[26:29], v[196:199], v[152:155], v[26:29]
	v_mfma_f32_16x16x32_bf16 v[22:25], v[196:199], v[156:159], v[22:25]
	v_mfma_f32_16x16x32_bf16 v[18:21], v[196:199], v[162:165], v[18:21]
	global_load_lds_dwordx4 v[134:135], off
	s_add_i32 m0, m0, 0x1000
	v_lshl_add_u64 v[132:133], v[132:133], 0, s[12:13]
	v_mfma_f32_16x16x32_bf16 v[14:17], v[196:199], v[166:169], v[14:17]
	v_mfma_f32_16x16x32_bf16 v[10:13], v[196:199], v[170:173], v[10:13]
	v_mfma_f32_16x16x32_bf16 v[6:9], v[196:199], v[176:179], v[6:9]
	global_load_lds_dwordx4 v[142:143], off
	v_lshl_add_u64 v[134:135], v[134:135], 0, s[4:5]
	v_mfma_f32_16x16x32_bf16 v[2:5], v[196:199], v[180:183], v[2:5]
	s_mov_b32 s41, s40
	s_nop 0
	s_add_i32 s40, s40, 0x6000
	s_cmp_eq_u32 s40, 0x12000
	s_cselect_b32 s40, 0, s40
	s_nop 0
	.p2align 3
	s_waitcnt vmcnt(6) lgkmcnt(0)
	s_barrier
	s_setprio 2
	v_add_u32_e32 v144, s40, v136
	v_mfma_f32_16x16x32_bf16 v[126:129], v[232:235], v[200:203], v[126:129]
	ds_read_b128 v[146:149], v144 offset:0
	v_mfma_f32_16x16x32_bf16 v[122:125], v[232:235], v[204:207], v[122:125]
	ds_read_b128 v[152:155], v144 offset:1024
	v_mfma_f32_16x16x32_bf16 v[118:121], v[232:235], v[208:211], v[118:121]
	ds_read_b128 v[156:159], v144 offset:2048
	v_mfma_f32_16x16x32_bf16 v[114:117], v[232:235], v[212:215], v[114:117]
	ds_read_b128 v[162:165], v144 offset:3072
	v_mfma_f32_16x16x32_bf16 v[110:113], v[232:235], v[216:219], v[110:113]
	ds_read_b128 v[166:169], v144 offset:4096
	v_mfma_f32_16x16x32_bf16 v[106:109], v[232:235], v[220:223], v[106:109]
	ds_read_b128 v[170:173], v144 offset:5120
	v_mfma_f32_16x16x32_bf16 v[102:105], v[232:235], v[224:227], v[102:105]
	ds_read_b128 v[176:179], v144 offset:6144
	v_mfma_f32_16x16x32_bf16 v[98:101], v[232:235], v[228:231], v[98:101]
	ds_read_b128 v[180:183], v144 offset:7168
	v_mfma_f32_16x16x32_bf16 v[94:97], v[236:239], v[200:203], v[94:97]
	v_add_u32_e64 v144, s40, v137
	v_mfma_f32_16x16x32_bf16 v[90:93], v[236:239], v[204:207], v[90:93]
	v_mfma_f32_16x16x32_bf16 v[86:89], v[236:239], v[208:211], v[86:89]
	ds_read_b128 v[184:187], v144 offset:16384
	v_mfma_f32_16x16x32_bf16 v[82:85], v[236:239], v[212:215], v[82:85]
	ds_read_b128 v[188:191], v144 offset:17408
	v_mfma_f32_16x16x32_bf16 v[78:81], v[236:239], v[216:219], v[78:81]
	ds_read_b128 v[192:195], v144 offset:18432
	v_mfma_f32_16x16x32_bf16 v[74:77], v[236:239], v[220:223], v[74:77]
	ds_read_b128 v[196:199], v144 offset:19456
	v_mfma_f32_16x16x32_bf16 v[70:73], v[236:239], v[224:227], v[70:73]
	s_add_i32 s42, s46, s41
	s_mov_b32 m0, s42
	v_lshl_add_u64 v[142:143], v[132:133], 0, s[2:3]
	v_mfma_f32_16x16x32_bf16 v[66:69], v[236:239], v[228:231], v[66:69]
;     ...
;   __syncthreads();
;   G2_STAGE(0); G2_STAGE(1);
;   const int fsw = (0x78 >> (((r16 >> 2) & 3) * 2)) & 3;
;   const int aoff = (wm * 128 + r16) * 64 + ((quad ^ fsw) << 4);
;   const int boff = 16384 + (wn * 64 + r16) * 64 + ((quad ^ fsw) << 4);
;   for (int kt = 0; kt < nk; kt++) {
;     if (kt + 1 < nk) asm volatile("s_waitcnt vmcnt(6)" ::: "memory");
;     else asm volatile("s_waitcnt vmcnt(0)" ::: "memory");
;     __builtin_amdgcn_s_barrier();
;     asm volatile("" ::: "memory");
;     if (kt + 2 < nk) G2_STAGE(kt + 2);
;     const char* cS = smem + (kt % 3) * 24576;
;     bf16x8 xa[8], wb[4];
; #pragma unroll
;     for (int f = 0; f < 8; f++) xa[f] = *(const bf16x8*)(cS + aoff + f * 1024);
; #pragma unroll
;     for (int f = 0; f < 4; f++) wb[f] = *(const bf16x8*)(cS + boff + f * 1024);
; #pragma unroll
;     for (int nf = 0; nf < 4; nf++)
; #pragma unroll
;       for (int mf = 0; mf < 8; mf++)
;         acc[nf][mf] = __builtin_amdgcn_mfma_f32_16x16x32_bf16(wb[nf], xa[mf], acc[nf][mf], 0, 0, 0);
;   }
	global_load_lds_dwordx4 v[132:133], off
	s_add_i32 m0, m0, 0x1000
	v_mfma_f32_16x16x32_bf16 v[62:65], v[240:243], v[200:203], v[62:65]
	v_mfma_f32_16x16x32_bf16 v[58:61], v[240:243], v[204:207], v[58:61]
	v_mfma_f32_16x16x32_bf16 v[54:57], v[240:243], v[208:211], v[54:57]
	global_load_lds_dwordx4 v[142:143], off
	v_lshl_add_u64 v[142:143], v[142:143], 0, s[2:3]
	s_add_i32 m0, m0, 0x1000
	v_mfma_f32_16x16x32_bf16 v[50:53], v[240:243], v[212:215], v[50:53]
	v_mfma_f32_16x16x32_bf16 v[46:49], v[240:243], v[216:219], v[46:49]
	v_mfma_f32_16x16x32_bf16 v[42:45], v[240:243], v[220:223], v[42:45]
	global_load_lds_dwordx4 v[142:143], off
	v_lshl_add_u64 v[142:143], v[142:143], 0, s[2:3]
	s_add_i32 m0, m0, 0x1000
	v_mfma_f32_16x16x32_bf16 v[38:41], v[240:243], v[224:227], v[38:41]
	v_mfma_f32_16x16x32_bf16 v[34:37], v[240:243], v[228:231], v[34:37]
	s_setprio 0
	s_nop 0
	v_mfma_f32_16x16x32_bf16 v[30:33], v[244:247], v[200:203], v[30:33]
	global_load_lds_dwordx4 v[142:143], off
	s_add_i32 m0, m0, 0x1000
	v_lshl_add_u64 v[142:143], v[134:135], 0, s[2:3]
	v_mfma_f32_16x16x32_bf16 v[26:29], v[244:247], v[204:207], v[26:29]
	v_mfma_f32_16x16x32_bf16 v[22:25], v[244:247], v[208:211], v[22:25]
	v_mfma_f32_16x16x32_bf16 v[18:21], v[244:247], v[212:215], v[18:21]
	global_load_lds_dwordx4 v[134:135], off
	s_add_i32 m0, m0, 0x1000
	v_lshl_add_u64 v[132:133], v[132:133], 0, s[12:13]
	v_mfma_f32_16x16x32_bf16 v[14:17], v[244:247], v[216:219], v[14:17]
	v_mfma_f32_16x16x32_bf16 v[10:13], v[244:247], v[220:223], v[10:13]
	v_mfma_f32_16x16x32_bf16 v[6:9], v[244:247], v[224:227], v[6:9]
	global_load_lds_dwordx4 v[142:143], off
	v_lshl_add_u64 v[134:135], v[134:135], 0, s[4:5]
	v_mfma_f32_16x16x32_bf16 v[2:5], v[244:247], v[228:231], v[2:5]
	s_mov_b32 s41, s40
	s_nop 0
	s_add_i32 s40, s40, 0x6000
	s_cmp_eq_u32 s40, 0x12000
	s_cselect_b32 s40, 0, s40
	s_nop 0
	s_sub_i32 s39, s39, 1
	s_cmp_lg_u32 s39, 0
	s_cbranch_scc1 .Lta11_loop
	.p2align 3
	s_waitcnt vmcnt(6) lgkmcnt(0)
	s_barrier
	s_setprio 2
	v_add_u32_e32 v144, s40, v136
	v_mfma_f32_16x16x32_bf16 v[126:129], v[184:187], v[146:149], v[126:129]
	ds_read_b128 v[200:203], v144 offset:0
	v_mfma_f32_16x16x32_bf16 v[122:125], v[184:187], v[152:155], v[122:125]
	ds_read_b128 v[204:207], v144 offset:1024
	v_mfma_f32_16x16x32_bf16 v[118:121], v[184:187], v[156:159], v[118:121]
	ds_read_b128 v[208:211], v144 offset:2048
	v_mfma_f32_16x16x32_bf16 v[114:117], v[184:187], v[162:165], v[114:117]
	ds_read_b128 v[212:215], v144 offset:3072
	v_mfma_f32_16x16x32_bf16 v[110:113], v[184:187], v[166:169], v[110:113]
	ds_read_b128 v[216:219], v144 offset:4096
	v_mfma_f32_16x16x32_bf16 v[106:109], v[184:187], v[170:173], v[106:109]
	ds_read_b128 v[220:223], v144 offset:5120
	v_mfma_f32_16x16x32_bf16 v[102:105], v[184:187], v[176:179], v[102:105]
	ds_read_b128 v[224:227], v144 offset:6144
	v_mfma_f32_16x16x32_bf16 v[98:101], v[184:187], v[180:183], v[98:101]
	ds_read_b128 v[228:231], v144 offset:7168
	v_mfma_f32_16x16x32_bf16 v[94:97], v[188:191], v[146:149], v[94:97]
	v_add_u32_e64 v144, s40, v137
	v_mfma_f32_16x16x32_bf16 v[90:93], v[188:191], v[152:155], v[90:93]
	v_mfma_f32_16x16x32_bf16 v[86:89], v[188:191], v[156:159], v[86:89]
	ds_read_b128 v[232:235], v144 offset:16384
	v_mfma_f32_16x16x32_bf16 v[82:85], v[188:191], v[162:165], v[82:85]
	ds_read_b128 v[236:239], v144 offset:17408
	v_mfma_f32_16x16x32_bf16 v[78:81], v[188:191], v[166:169], v[78:81]
	ds_read_b128 v[240:243], v144 offset:18432
	v_mfma_f32_16x16x32_bf16 v[74:77], v[188:191], v[170:173], v[74:77]
	ds_read_b128 v[244:247], v144 offset:19456
	v_mfma_f32_16x16x32_bf16 v[70:73], v[188:191], v[176:179], v[70:73]
	s_add_i32 s42, s46, s41
	s_mov_b32 m0, s42
	v_lshl_add_u64 v[142:143], v[132:133], 0, s[2:3]
	v_mfma_f32_16x16x32_bf16 v[66:69], v[188:191], v[180:183], v[66:69]
	global_load_lds_dwordx4 v[132:133], off
	s_add_i32 m0, m0, 0x1000
	v_mfma_f32_16x16x32_bf16 v[62:65], v[192:195], v[146:149], v[62:65]
	v_mfma_f32_16x16x32_bf16 v[58:61], v[192:195], v[152:155], v[58:61]
	v_mfma_f32_16x16x32_bf16 v[54:57], v[192:195], v[156:159], v[54:57]
	global_load_lds_dwordx4 v[142:143], off
	v_lshl_add_u64 v[142:143], v[142:143], 0, s[2:3]
	s_add_i32 m0, m0, 0x1000
	v_mfma_f32_16x16x32_bf16 v[50:53], v[192:195], v[162:165], v[50:53]
	v_mfma_f32_16x16x32_bf16 v[46:49], v[192:195], v[166:169], v[46:49]
	v_mfma_f32_16x16x32_bf16 v[42:45], v[192:195], v[170:173], v[42:45]
	global_load_lds_dwordx4 v[142:143], off
	v_lshl_add_u64 v[142:143], v[142:143], 0, s[2:3]
	s_add_i32 m0, m0, 0x1000
	v_mfma_f32_16x16x32_bf16 v[38:41], v[192:195], v[176:179], v[38:41]
	v_mfma_f32_16x16x32_bf16 v[34:37], v[192:195], v[180:183], v[34:37]
	s_setprio 0
	s_nop 0
	v_mfma_f32_16x16x32_bf16 v[30:33], v[196:199], v[146:149], v[30:33]
	global_load_lds_dwordx4 v[142:143], off
	s_add_i32 m0, m0, 0x1000
	v_lshl_add_u64 v[142:143], v[134:135], 0, s[2:3]
	v_mfma_f32_16x16x32_bf16 v[26:29], v[196:199], v[152:155], v[26:29]
	v_mfma_f32_16x16x32_bf16 v[22:25], v[196:199], v[156:159], v[22:25]
	v_mfma_f32_16x16x32_bf16 v[18:21], v[196:199], v[162:165], v[18:21]
	global_load_lds_dwordx4 v[134:135], off
	s_add_i32 m0, m0, 0x1000
	v_lshl_add_u64 v[132:133], v[132:133], 0, s[12:13]
	v_mfma_f32_16x16x32_bf16 v[14:17], v[196:199], v[166:169], v[14:17]
	v_mfma_f32_16x16x32_bf16 v[10:13], v[196:199], v[170:173], v[10:13]
	v_mfma_f32_16x16x32_bf16 v[6:9], v[196:199], v[176:179], v[6:9]
	global_load_lds_dwordx4 v[142:143], off
	v_lshl_add_u64 v[134:135], v[134:135], 0, s[4:5]
	v_mfma_f32_16x16x32_bf16 v[2:5], v[196:199], v[180:183], v[2:5]
	s_mov_b32 s41, s40
	s_nop 0
	s_add_i32 s40, s40, 0x6000
	s_cmp_eq_u32 s40, 0x12000
	s_cselect_b32 s40, 0, s40
	s_nop 0
	.p2align 3
	s_waitcnt vmcnt(6) lgkmcnt(0)
	s_barrier
;     ...
;   for (int kt = 0; kt < nk; kt++) {
;     if (kt + 1 < nk) asm volatile("s_waitcnt vmcnt(6)" ::: "memory");
;     else asm volatile("s_waitcnt vmcnt(0)" ::: "memory");
;     __builtin_amdgcn_s_barrier();
;     asm volatile("" ::: "memory");
;     if (kt + 2 < nk) G2_STAGE(kt + 2);
;     const char* cS = smem + (kt % 3) * 24576;
;     bf16x8 xa[8], wb[4];
; #pragma unroll
;     for (int f = 0; f < 8; f++) xa[f] = *(const bf16x8*)(cS + aoff + f * 1024);
; #pragma unroll
;     for (int f = 0; f < 4; f++) wb[f] = *(const bf16x8*)(cS + boff + f * 1024);
; #pragma unroll
;     for (int nf = 0; nf < 4; nf++)
; #pragma unroll
;       for (int mf = 0; mf < 8; mf++)
;         acc[nf][mf] = __builtin_amdgcn_mfma_f32_16x16x32_bf16(wb[nf], xa[mf], acc[nf][mf], 0, 0, 0);
;   }
	s_setprio 2
	v_add_u32_e32 v144, s40, v136
	v_mfma_f32_16x16x32_bf16 v[126:129], v[232:235], v[200:203], v[126:129]
	ds_read_b128 v[146:149], v144 offset:0
	v_mfma_f32_16x16x32_bf16 v[122:125], v[232:235], v[204:207], v[122:125]
	ds_read_b128 v[152:155], v144 offset:1024
	v_mfma_f32_16x16x32_bf16 v[118:121], v[232:235], v[208:211], v[118:121]
	ds_read_b128 v[156:159], v144 offset:2048
	v_mfma_f32_16x16x32_bf16 v[114:117], v[232:235], v[212:215], v[114:117]
	ds_read_b128 v[162:165], v144 offset:3072
	v_mfma_f32_16x16x32_bf16 v[110:113], v[232:235], v[216:219], v[110:113]
	ds_read_b128 v[166:169], v144 offset:4096
	v_mfma_f32_16x16x32_bf16 v[106:109], v[232:235], v[220:223], v[106:109]
	ds_read_b128 v[170:173], v144 offset:5120
	v_mfma_f32_16x16x32_bf16 v[102:105], v[232:235], v[224:227], v[102:105]
	ds_read_b128 v[176:179], v144 offset:6144
	v_mfma_f32_16x16x32_bf16 v[98:101], v[232:235], v[228:231], v[98:101]
	ds_read_b128 v[180:183], v144 offset:7168
	v_mfma_f32_16x16x32_bf16 v[94:97], v[236:239], v[200:203], v[94:97]
	v_add_u32_e64 v144, s40, v137
	v_mfma_f32_16x16x32_bf16 v[90:93], v[236:239], v[204:207], v[90:93]
	v_mfma_f32_16x16x32_bf16 v[86:89], v[236:239], v[208:211], v[86:89]
	ds_read_b128 v[184:187], v144 offset:16384
	v_mfma_f32_16x16x32_bf16 v[82:85], v[236:239], v[212:215], v[82:85]
	ds_read_b128 v[188:191], v144 offset:17408
	v_mfma_f32_16x16x32_bf16 v[78:81], v[236:239], v[216:219], v[78:81]
	ds_read_b128 v[192:195], v144 offset:18432
	v_mfma_f32_16x16x32_bf16 v[74:77], v[236:239], v[220:223], v[74:77]
	ds_read_b128 v[196:199], v144 offset:19456
	v_mfma_f32_16x16x32_bf16 v[70:73], v[236:239], v[224:227], v[70:73]
	v_mfma_f32_16x16x32_bf16 v[66:69], v[236:239], v[228:231], v[66:69]
	v_mfma_f32_16x16x32_bf16 v[62:65], v[240:243], v[200:203], v[62:65]
	v_mfma_f32_16x16x32_bf16 v[58:61], v[240:243], v[204:207], v[58:61]
	v_mfma_f32_16x16x32_bf16 v[54:57], v[240:243], v[208:211], v[54:57]
	v_mfma_f32_16x16x32_bf16 v[50:53], v[240:243], v[212:215], v[50:53]
	v_mfma_f32_16x16x32_bf16 v[46:49], v[240:243], v[216:219], v[46:49]
	v_mfma_f32_16x16x32_bf16 v[42:45], v[240:243], v[220:223], v[42:45]
	v_mfma_f32_16x16x32_bf16 v[38:41], v[240:243], v[224:227], v[38:41]
	v_mfma_f32_16x16x32_bf16 v[34:37], v[240:243], v[228:231], v[34:37]
	s_setprio 0
	s_nop 0
	v_mfma_f32_16x16x32_bf16 v[30:33], v[244:247], v[200:203], v[30:33]
	v_mfma_f32_16x16x32_bf16 v[26:29], v[244:247], v[204:207], v[26:29]
	v_mfma_f32_16x16x32_bf16 v[22:25], v[244:247], v[208:211], v[22:25]
	v_mfma_f32_16x16x32_bf16 v[18:21], v[244:247], v[212:215], v[18:21]
	v_mfma_f32_16x16x32_bf16 v[14:17], v[244:247], v[216:219], v[14:17]
	v_mfma_f32_16x16x32_bf16 v[10:13], v[244:247], v[220:223], v[10:13]
	v_mfma_f32_16x16x32_bf16 v[6:9], v[244:247], v[224:227], v[6:9]
	v_mfma_f32_16x16x32_bf16 v[2:5], v[244:247], v[228:231], v[2:5]
	s_mov_b32 s41, s40
	s_nop 0
	s_add_i32 s40, s40, 0x6000
	s_cmp_eq_u32 s40, 0x12000
	s_cselect_b32 s40, 0, s40
	s_nop 0
	.p2align 3
	s_waitcnt vmcnt(0) lgkmcnt(0)
	s_barrier
	s_setprio 2
	v_add_u32_e32 v144, s40, v136
	v_mfma_f32_16x16x32_bf16 v[126:129], v[184:187], v[146:149], v[126:129]
	ds_read_b128 v[200:203], v144 offset:0
	v_mfma_f32_16x16x32_bf16 v[122:125], v[184:187], v[152:155], v[122:125]
	ds_read_b128 v[204:207], v144 offset:1024
	v_mfma_f32_16x16x32_bf16 v[118:121], v[184:187], v[156:159], v[118:121]
	ds_read_b128 v[208:211], v144 offset:2048
	v_mfma_f32_16x16x32_bf16 v[114:117], v[184:187], v[162:165], v[114:117]
	ds_read_b128 v[212:215], v144 offset:3072
	v_mfma_f32_16x16x32_bf16 v[110:113], v[184:187], v[166:169], v[110:113]
	ds_read_b128 v[216:219], v144 offset:4096
	v_mfma_f32_16x16x32_bf16 v[106:109], v[184:187], v[170:173], v[106:109]
	ds_read_b128 v[220:223], v144 offset:5120
	v_mfma_f32_16x16x32_bf16 v[102:105], v[184:187], v[176:179], v[102:105]
	ds_read_b128 v[224:227], v144 offset:6144
	v_mfma_f32_16x16x32_bf16 v[98:101], v[184:187], v[180:183], v[98:101]
	ds_read_b128 v[228:231], v144 offset:7168
	v_mfma_f32_16x16x32_bf16 v[94:97], v[188:191], v[146:149], v[94:97]
	v_add_u32_e64 v144, s40, v137
	v_mfma_f32_16x16x32_bf16 v[90:93], v[188:191], v[152:155], v[90:93]
	v_mfma_f32_16x16x32_bf16 v[86:89], v[188:191], v[156:159], v[86:89]
	ds_read_b128 v[232:235], v144 offset:16384
	v_mfma_f32_16x16x32_bf16 v[82:85], v[188:191], v[162:165], v[82:85]
	ds_read_b128 v[236:239], v144 offset:17408
	v_mfma_f32_16x16x32_bf16 v[78:81], v[188:191], v[166:169], v[78:81]
	ds_read_b128 v[240:243], v144 offset:18432
	v_mfma_f32_16x16x32_bf16 v[74:77], v[188:191], v[170:173], v[74:77]
	ds_read_b128 v[244:247], v144 offset:19456
	v_mfma_f32_16x16x32_bf16 v[70:73], v[188:191], v[176:179], v[70:73]
	v_mfma_f32_16x16x32_bf16 v[66:69], v[188:191], v[180:183], v[66:69]
	v_mfma_f32_16x16x32_bf16 v[62:65], v[192:195], v[146:149], v[62:65]
	v_mfma_f32_16x16x32_bf16 v[58:61], v[192:195], v[152:155], v[58:61]
	v_mfma_f32_16x16x32_bf16 v[54:57], v[192:195], v[156:159], v[54:57]
	v_mfma_f32_16x16x32_bf16 v[50:53], v[192:195], v[162:165], v[50:53]
	v_mfma_f32_16x16x32_bf16 v[46:49], v[192:195], v[166:169], v[46:49]
	v_mfma_f32_16x16x32_bf16 v[42:45], v[192:195], v[170:173], v[42:45]
	v_mfma_f32_16x16x32_bf16 v[38:41], v[192:195], v[176:179], v[38:41]
	v_mfma_f32_16x16x32_bf16 v[34:37], v[192:195], v[180:183], v[34:37]
	s_setprio 0
	s_nop 0
	v_mfma_f32_16x16x32_bf16 v[30:33], v[196:199], v[146:149], v[30:33]
	v_mfma_f32_16x16x32_bf16 v[26:29], v[196:199], v[152:155], v[26:29]
	v_mfma_f32_16x16x32_bf16 v[22:25], v[196:199], v[156:159], v[22:25]
	v_mfma_f32_16x16x32_bf16 v[18:21], v[196:199], v[162:165], v[18:21]
	v_mfma_f32_16x16x32_bf16 v[14:17], v[196:199], v[166:169], v[14:17]
	v_mfma_f32_16x16x32_bf16 v[10:13], v[196:199], v[170:173], v[10:13]
	v_mfma_f32_16x16x32_bf16 v[6:9], v[196:199], v[176:179], v[6:9]
	v_mfma_f32_16x16x32_bf16 v[2:5], v[196:199], v[180:183], v[2:5]
	s_mov_b32 s41, s40
	s_nop 0
	s_add_i32 s40, s40, 0x6000
	s_cmp_eq_u32 s40, 0x12000
	s_cselect_b32 s40, 0, s40
	s_nop 0
	s_mov_b32 s4, 0x8000
	s_mov_b32 s5, 0
	s_mov_b32 s10, 0x10000
	s_mov_b32 s11, 0
	s_mov_b32 s44, 0x3fd744fd
	.p2align 3
	s_waitcnt lgkmcnt(0)
; DEVI float blo(unsigned u) { return __uint_as_float(u << 16); }
; DEVI float bhi(unsigned u) { return __uint_as_float(u & 0xffff0000u); }
;     ...
;     for (int nf = 0; nf < 4; nf++)
; #pragma unroll
;       for (int mf = 0; mf < 8; mf++)
;         acc[nf][mf] = __builtin_amdgcn_mfma_f32_16x16x32_bf16(wb[nf], xa[mf], acc[nf][mf], 0, 0, 0);
;     ...
; #pragma unroll
;       for (int nf = 0; nf < 4; nf++) {
;         const int col = n0 + wn * 64 + nf * 16 + quad * 4;
;         f32x4 a = acc[nf][mf];
;         if (EPI == EPI_RESID || EPI == EPI_RESID_ATOMIC) {
;           f32x4 x = a;
;           if (EPI == EPI_RESID || kpart == 0) {
;             const u32x2 xr = *(const u32x2*)((const u16*)(p.ws + WS_XB) + (size_t)row * 1024 + col);
;             x[0] += ALPHA * blo(xr[0]); x[1] += ALPHA * bhi(xr[0]); x[2] += ALPHA * blo(xr[1]); x[3] += ALPHA * bhi(xr[1]);
;           }
;           if (EPI == EPI_RESID) *(f32x4*)((float*)(p.ws + WS_XF) + (size_t)row * 1024 + col) = x;
;           else *(f32x4*)((float*)(p.ws + WS_SLAB) + ((size_t)kpart * 512 + (row - T_P)) * 1024 + col) = x;
	s_nop 0
	v_mfma_f32_16x16x32_bf16 v[126:129], v[232:235], v[200:203], v[126:129]
	v_mfma_f32_16x16x32_bf16 v[122:125], v[232:235], v[204:207], v[122:125]
	v_mfma_f32_16x16x32_bf16 v[118:121], v[232:235], v[208:211], v[118:121]
	v_mfma_f32_16x16x32_bf16 v[114:117], v[232:235], v[212:215], v[114:117]
	v_mfma_f32_16x16x32_bf16 v[110:113], v[232:235], v[216:219], v[110:113]
	v_mfma_f32_16x16x32_bf16 v[106:109], v[232:235], v[220:223], v[106:109]
	v_mfma_f32_16x16x32_bf16 v[102:105], v[232:235], v[224:227], v[102:105]
	v_mfma_f32_16x16x32_bf16 v[98:101], v[232:235], v[228:231], v[98:101]
	v_mfma_f32_16x16x32_bf16 v[94:97], v[236:239], v[200:203], v[94:97]
	v_mfma_f32_16x16x32_bf16 v[90:93], v[236:239], v[204:207], v[90:93]
	v_mfma_f32_16x16x32_bf16 v[86:89], v[236:239], v[208:211], v[86:89]
	v_mfma_f32_16x16x32_bf16 v[82:85], v[236:239], v[212:215], v[82:85]
	v_mfma_f32_16x16x32_bf16 v[78:81], v[236:239], v[216:219], v[78:81]
	v_mfma_f32_16x16x32_bf16 v[74:77], v[236:239], v[220:223], v[74:77]
	v_mfma_f32_16x16x32_bf16 v[70:73], v[236:239], v[224:227], v[70:73]
	v_mfma_f32_16x16x32_bf16 v[66:69], v[236:239], v[228:231], v[66:69]
	v_mfma_f32_16x16x32_bf16 v[62:65], v[240:243], v[200:203], v[62:65]
	v_mfma_f32_16x16x32_bf16 v[58:61], v[240:243], v[204:207], v[58:61]
	v_mfma_f32_16x16x32_bf16 v[54:57], v[240:243], v[208:211], v[54:57]
	v_mfma_f32_16x16x32_bf16 v[50:53], v[240:243], v[212:215], v[50:53]
	v_mfma_f32_16x16x32_bf16 v[46:49], v[240:243], v[216:219], v[46:49]
	v_mfma_f32_16x16x32_bf16 v[42:45], v[240:243], v[220:223], v[42:45]
	v_mfma_f32_16x16x32_bf16 v[38:41], v[240:243], v[224:227], v[38:41]
	v_mfma_f32_16x16x32_bf16 v[34:37], v[240:243], v[228:231], v[34:37]
	v_mfma_f32_16x16x32_bf16 v[30:33], v[244:247], v[200:203], v[30:33]
	v_mfma_f32_16x16x32_bf16 v[26:29], v[244:247], v[204:207], v[26:29]
	v_mfma_f32_16x16x32_bf16 v[22:25], v[244:247], v[208:211], v[22:25]
	v_mfma_f32_16x16x32_bf16 v[18:21], v[244:247], v[212:215], v[18:21]
	v_mfma_f32_16x16x32_bf16 v[14:17], v[244:247], v[216:219], v[14:17]
	v_mfma_f32_16x16x32_bf16 v[10:13], v[244:247], v[220:223], v[10:13]
	v_mfma_f32_16x16x32_bf16 v[6:9], v[244:247], v[224:227], v[6:9]
	v_mfma_f32_16x16x32_bf16 v[2:5], v[244:247], v[228:231], v[2:5]
	s_mov_b32 m0, s43
	s_cmp_eq_u32 s47, 0
	s_cbranch_scc1 .Lta11_first
	s_nop 7
	global_store_dwordx4 v[140:141], v[126:129], off offset:0
	global_store_dwordx4 v[140:141], v[94:97], off offset:64
	global_store_dwordx4 v[140:141], v[62:65], off offset:128
	global_store_dwordx4 v[140:141], v[30:33], off offset:192
	v_lshl_add_u64 v[140:141], v[140:141], 0, s[10:11]
	global_store_dwordx4 v[140:141], v[122:125], off offset:0
	global_store_dwordx4 v[140:141], v[90:93], off offset:64
	global_store_dwordx4 v[140:141], v[58:61], off offset:128
	global_store_dwordx4 v[140:141], v[26:29], off offset:192
	v_lshl_add_u64 v[140:141], v[140:141], 0, s[10:11]
	global_store_dwordx4 v[140:141], v[118:121], off offset:0
	global_store_dwordx4 v[140:141], v[86:89], off offset:64
	global_store_dwordx4 v[140:141], v[54:57], off offset:128
	global_store_dwordx4 v[140:141], v[22:25], off offset:192
	v_lshl_add_u64 v[140:141], v[140:141], 0, s[10:11]
	global_store_dwordx4 v[140:141], v[114:117], off offset:0
	global_store_dwordx4 v[140:141], v[82:85], off offset:64
	global_store_dwordx4 v[140:141], v[50:53], off offset:128
	global_store_dwordx4 v[140:141], v[18:21], off offset:192
	v_lshl_add_u64 v[140:141], v[140:141], 0, s[10:11]
	global_store_dwordx4 v[140:141], v[110:113], off offset:0
	global_store_dwordx4 v[140:141], v[78:81], off offset:64
	global_store_dwordx4 v[140:141], v[46:49], off offset:128
	global_store_dwordx4 v[140:141], v[14:17], off offset:192
	v_lshl_add_u64 v[140:141], v[140:141], 0, s[10:11]
	global_store_dwordx4 v[140:141], v[106:109], off offset:0
	global_store_dwordx4 v[140:141], v[74:77], off offset:64
	global_store_dwordx4 v[140:141], v[42:45], off offset:128
	global_store_dwordx4 v[140:141], v[10:13], off offset:192
	v_lshl_add_u64 v[140:141], v[140:141], 0, s[10:11]
	global_store_dwordx4 v[140:141], v[102:105], off offset:0
	global_store_dwordx4 v[140:141], v[70:73], off offset:64
	global_store_dwordx4 v[140:141], v[38:41], off offset:128
	global_store_dwordx4 v[140:141], v[6:9], off offset:192
	v_lshl_add_u64 v[140:141], v[140:141], 0, s[10:11]
	global_store_dwordx4 v[140:141], v[98:101], off offset:0
	global_store_dwordx4 v[140:141], v[66:69], off offset:64
	global_store_dwordx4 v[140:141], v[34:37], off offset:128
	global_store_dwordx4 v[140:141], v[2:5], off offset:192
	v_readlane_b32 s39, v250, 7
	s_cmpk_lg_u32 s39, 0x200
	s_cbranch_scc1 .Lta11_ar1
	s_mov_b32 s39, 1
	v_writelane_b32 v255, s39, 41
	v_readlane_b32 s40, v250, 0
	s_lshr_b32 s41, s40, 3
	s_and_b32 s40, s40, 7
	s_lshl_b32 s40, s40, 6
	s_add_i32 s40, s40, s41
	s_sub_i32 s38, s40, 0x200

; #define LAS __attribute__((address_space(3)))
;     ...
;   const int nk = (nk_part < 0) ? (K >> 5) : nk_part;
;   const int lrow = tid >> 2, lpc = tid & 3;
;   const int lch = lpc ^ ((0x78 >> (((lrow >> 2) & 3) * 2)) & 3);
;   const u16* ga = A + (size_t)(m0 + lrow) * lda + kbeg + lch * 8;
;   const u16* gb = Bt + (size_t)(n0 + lrow) * K + kbeg + lch * 8;
;   const size_t ga1 = (size_t)64 * lda, gb1 = (size_t)64 * K;
;   const unsigned lds0 = (unsigned)(uintptr_t)(LAS char*)smem + (unsigned)__builtin_amdgcn_readfirstlane(wid) * 1024u;
;     ...
;   __syncthreads();
;   G2_STAGE(0); G2_STAGE(1);
; DEVI void run_phase(const Params& p, int ph, char* smem) {
;     ...
;           const int u_ = t - 512, tl_ = u_ / 2, q_ = u_ - tl_ * 2;
;           gemm_tile256<EPI_RESID_ATOMIC>(p, ox, 256, Bt, 256, (64 + (tl_ & 1)) * 256, (tl_ >> 1) * 128, nullptr, 0, smem, q_ * 128, 4, q_);
.LBB0_147:
	s_cmpk_gt_i32 s38, 0x1ff
	s_mov_b64 s[2:3], -1
	s_cbranch_scc0 .LBB0_208
	s_setprio 2
	s_sub_i32 s98, s38, 512
	s_lshr_b32 s41, s98, 1
	s_and_b32 s99, s98, 1
	s_lshr_b32 s13, s41, 1
	s_and_b32 s41, s41, 1
	s_add_i32 s41, s41, 64
	v_readlane_b32 s2, v250, 5
	v_readlane_b32 s3, v250, 6
	v_readlane_b32 s98, v254, 62
	s_mul_i32 s1, s41, 0x20000
	s_add_u32 s4, s2, s1
	s_addc_u32 s5, s3, 0
	s_add_u32 s4, s4, 0xe700000
	s_addc_u32 s5, s5, 0
	s_mul_i32 s1, s98, 0x80000
	s_mul_i32 s12, s13, 0x10000
	s_add_i32 s1, s1, s12
	s_add_u32 s8, s2, s1
	s_addc_u32 s9, s3, 0
	s_add_u32 s8, s8, 0x16c00000
	s_addc_u32 s9, s9, 0
	s_mul_i32 s1, s99, 256
	s_add_u32 s4, s4, s1
	s_addc_u32 s5, s5, 0
	s_mul_i32 s1, s99, 512
	s_add_u32 s8, s8, s1
	s_addc_u32 s9, s9, 0
	s_movk_i32 s0, 0x78
	v_lshrrev_b32_e32 v0, 2, v145
	v_and_b32_e32 v131, 3, v145
	v_bfe_u32 v136, v145, 4, 2
	v_lshlrev_b32_e32 v136, 1, v136
	v_lshrrev_b32_e64 v136, v136, s0
	v_and_b32_e32 v136, 3, v136
	v_xor_b32_e32 v131, v131, v136
	v_lshlrev_b32_e32 v131, 4, v131
	s_movk_i32 s12, 0x200
	v_mad_u32_u24 v0, v0, s12, v131
	v_bfe_u32 v137, v145, 2, 1
	s_movk_i32 s12, 0x1c0
	v_mul_u32_u24_e32 v136, s12, v137
	v_sub_u32_e32 v136, v0, v136
	v_mov_b32_e32 v137, 0
	v_lshl_add_u64 v[134:135], s[8:9], 0, v[136:137]
	v_bfe_u32 v137, v145, 2, 1
	s_mov_b32 s10, 64
	s_mov_b32 s11, 0
	v_lshl_add_u64 v[132:133], s[4:5], 0, v[0:1]
	v_bfe_u32 v136, v145, 2, 2
	v_lshlrev_b32_e32 v136, 1, v136
	v_lshrrev_b32_e64 v136, v136, s0
	v_and_b32_e32 v136, 3, v136
	v_bfe_u32 v137, v145, 4, 2
	v_xor_b32_e32 v136, v136, v137
	v_lshlrev_b32_e32 v136, 4, v136
	v_and_b32_e32 v131, 15, v145
	v_lshl_or_b32 v136, v131, 6, v136
	v_bfe_u32 v137, v145, 6, 1
	v_lshl_or_b32 v137, v137, 12, v136
	v_lshrrev_b32_e32 v0, 7, v145
	v_lshl_or_b32 v136, v0, 13, v136
	v_and_b32_e32 v140, 1, v131
	v_lshl_or_b32 v131, v0, 7, v131
	v_bfe_u32 v0, v145, 4, 2
	v_lshlrev_b32_e32 v0, 3, v0
	v_bfe_u32 v141, v145, 6, 1
	s_lshl_b32 s1, s41, 19
	s_lshl_b32 s12, s13, 8
	s_add_i32 s1, s1, s12
	s_add_u32 s4, s2, s1
	s_addc_u32 s5, s3, 0
	s_add_u32 s4, s4, 0x4200000
	s_addc_u32 s5, s5, 0
	v_lshlrev_b32_e32 v138, 11, v131
	v_lshl_add_u32 v138, v141, 7, v138
	v_bfe_u32 v139, v145, 4, 1
	v_lshl_add_u32 v138, v139, 5, v138
	v_bfe_u32 v139, v145, 5, 1
	v_lshl_add_u32 v138, v139, 4, v138
	v_mov_b32_e32 v139, 0
	v_lshl_add_u64 v[138:139], s[4:5], 0, v[138:139]
	s_and_b32 s1, s41, 1
	s_lshl_b32 s1, s1, 20
	s_lshl_b32 s12, s99, 21
	s_add_i32 s1, s1, s12
	s_lshl_b32 s12, s13, 9
	s_add_i32 s1, s1, s12
	s_add_u32 s8, s2, s1
	s_addc_u32 s9, s3, 0
	s_add_u32 s8, s8, 0x1dcc0000
	s_addc_u32 s9, s9, 0
	v_lshlrev_b32_e32 v140, 12, v131
	v_lshl_add_u32 v140, v141, 8, v140
	v_lshl_add_u32 v140, v0, 1, v140
	v_mov_b32_e32 v141, 0
	v_lshl_add_u64 v[140:141], s[8:9], 0, v[140:141]
	s_mov_b32 s2, 0x8000
	s_mov_b32 s3, 0
	v_lshrrev_b32_e32 v0, 6, v145
	v_lshlrev_b32_e32 v0, 10, v0
	s_nop 0
	v_readfirstlane_b32 s98, v0
	s_mov_b32 s39, m0
	s_mov_b32 s4, 128
	s_mov_b32 s5, 0
	s_barrier
	s_add_i32 s13, s98, 0x0
	s_mov_b32 m0, s13
	v_lshl_add_u64 v[142:143], v[132:133], 0, s[2:3]
	global_load_lds_dwordx4 v[132:133], off
	s_add_i32 m0, m0, 0x1000
	s_nop 0
	global_load_lds_dwordx4 v[142:143], off
	v_lshl_add_u64 v[142:143], v[142:143], 0, s[2:3]
	s_add_i32 m0, m0, 0x1000
	s_nop 0
	global_load_lds_dwordx4 v[142:143], off
	v_lshl_add_u64 v[142:143], v[142:143], 0, s[2:3]
	s_add_i32 m0, m0, 0x1000
	s_nop 0
	global_load_lds_dwordx4 v[142:143], off
	s_add_i32 m0, m0, 0x1000
	v_lshl_add_u64 v[142:143], v[134:135], 0, s[2:3]
	s_nop 0
	global_load_lds_dwordx4 v[134:135], off
	s_add_i32 m0, m0, 0x1000
	v_lshl_add_u64 v[132:133], v[132:133], 0, s[10:11]
	s_nop 0
	global_load_lds_dwordx4 v[142:143], off
	v_lshl_add_u64 v[134:135], v[134:135], 0, s[4:5]
	s_nop 0
	s_add_i32 s13, s98, 0x6000
	s_mov_b32 m0, s13
	v_lshl_add_u64 v[142:143], v[132:133], 0, s[2:3]
	global_load_lds_dwordx4 v[132:133], off
	s_add_i32 m0, m0, 0x1000
	s_nop 0
	global_load_lds_dwordx4 v[142:143], off
	v_lshl_add_u64 v[142:143], v[142:143], 0, s[2:3]
	s_add_i32 m0, m0, 0x1000
	s_nop 0
	global_load_lds_dwordx4 v[142:143], off
	v_lshl_add_u64 v[142:143], v[142:143], 0, s[2:3]
	s_add_i32 m0, m0, 0x1000
	s_nop 0
	global_load_lds_dwordx4 v[142:143], off
	s_add_i32 m0, m0, 0x1000
	v_lshl_add_u64 v[142:143], v[134:135], 0, s[2:3]
	s_nop 0
	global_load_lds_dwordx4 v[134:135], off
	s_add_i32 m0, m0, 0x1000
	v_lshl_add_u64 v[132:133], v[132:133], 0, s[10:11]
	s_nop 0
	global_load_lds_dwordx4 v[142:143], off
	v_lshl_add_u64 v[134:135], v[134:135], 0, s[4:5]
	s_nop 0
	s_add_i32 s13, s98, 0xc000
	s_mov_b32 m0, s13
	v_lshl_add_u64 v[142:143], v[132:133], 0, s[2:3]
	global_load_lds_dwordx4 v[132:133], off
	s_add_i32 m0, m0, 0x1000
	s_nop 0
	global_load_lds_dwordx4 v[142:143], off
	v_lshl_add_u64 v[142:143], v[142:143], 0, s[2:3]
	s_add_i32 m0, m0, 0x1000
	s_nop 0
	global_load_lds_dwordx4 v[142:143], off
	v_lshl_add_u64 v[142:143], v[142:143], 0, s[2:3]
	s_add_i32 m0, m0, 0x1000
	s_nop 0
	global_load_lds_dwordx4 v[142:143], off
	s_add_i32 m0, m0, 0x1000
	v_lshl_add_u64 v[142:143], v[134:135], 0, s[2:3]
	s_nop 0
	global_load_lds_dwordx4 v[134:135], off
	s_add_i32 m0, m0, 0x1000
	v_lshl_add_u64 v[132:133], v[132:133], 0, s[10:11]
	s_nop 0
	global_load_lds_dwordx4 v[142:143], off
	v_lshl_add_u64 v[134:135], v[134:135], 0, s[4:5]
	s_nop 0
	v_mov_b32_e32 v2, 0
	v_mov_b32_e32 v3, 0
	v_mov_b32_e32 v4, 0
	v_mov_b32_e32 v5, 0
	v_mov_b32_e32 v6, 0
	v_mov_b32_e32 v7, 0
	v_mov_b32_e32 v8, 0
	v_mov_b32_e32 v9, 0
	v_mov_b32_e32 v10, 0
	v_mov_b32_e32 v11, 0
	v_mov_b32_e32 v12, 0
	v_mov_b32_e32 v13, 0
	v_mov_b32_e32 v14, 0
	v_mov_b32_e32 v15, 0
;     ...
;   f32x4 acc[4][8];
; #pragma unroll
;   for (int i = 0; i < 4; i++)
; #pragma unroll
;     for (int j = 0; j < 8; j++) acc[i][j] = (f32x4){0.f, 0.f, 0.f, 0.f};
;     ...
;   __syncthreads();
;   G2_STAGE(0); G2_STAGE(1);
;   const int fsw = (0x78 >> (((r16 >> 2) & 3) * 2)) & 3;
;   const int aoff = (wm * 128 + r16) * 64 + ((quad ^ fsw) << 4);
;   const int boff = 16384 + (wn * 64 + r16) * 64 + ((quad ^ fsw) << 4);
;   for (int kt = 0; kt < nk; kt++) {
;     if (kt + 1 < nk) asm volatile("s_waitcnt vmcnt(6)" ::: "memory");
;     else asm volatile("s_waitcnt vmcnt(0)" ::: "memory");
;     __builtin_amdgcn_s_barrier();
;     asm volatile("" ::: "memory");
;     if (kt + 2 < nk) G2_STAGE(kt + 2);
;     const char* cS = smem + (kt % 3) * 24576;
;     bf16x8 xa[8], wb[4];
; #pragma unroll
;     for (int f = 0; f < 8; f++) xa[f] = *(const bf16x8*)(cS + aoff + f * 1024);
; #pragma unroll
;     for (int f = 0; f < 4; f++) wb[f] = *(const bf16x8*)(cS + boff + f * 1024);
; #pragma unroll
;     for (int nf = 0; nf < 4; nf++)
; #pragma unroll
;       for (int mf = 0; mf < 8; mf++)
;         acc[nf][mf] = __builtin_amdgcn_mfma_f32_16x16x32_bf16(wb[nf], xa[mf], acc[nf][mf], 0, 0, 0);
	v_mov_b32_e32 v16, 0
	v_mov_b32_e32 v17, 0
	v_mov_b32_e32 v18, 0
	v_mov_b32_e32 v19, 0
	v_mov_b32_e32 v20, 0
	v_mov_b32_e32 v21, 0
	v_mov_b32_e32 v22, 0
	v_mov_b32_e32 v23, 0
	v_mov_b32_e32 v24, 0
	v_mov_b32_e32 v25, 0
	v_mov_b32_e32 v26, 0
	v_mov_b32_e32 v27, 0
	v_mov_b32_e32 v28, 0
	v_mov_b32_e32 v29, 0
	v_mov_b32_e32 v30, 0
	v_mov_b32_e32 v31, 0
	v_mov_b32_e32 v32, 0
	v_mov_b32_e32 v33, 0
	v_mov_b32_e32 v34, 0
	v_mov_b32_e32 v35, 0
	v_mov_b32_e32 v36, 0
	v_mov_b32_e32 v37, 0
	v_mov_b32_e32 v38, 0
	v_mov_b32_e32 v39, 0
	v_mov_b32_e32 v40, 0
	v_mov_b32_e32 v41, 0
	v_mov_b32_e32 v42, 0
	v_mov_b32_e32 v43, 0
	v_mov_b32_e32 v44, 0
	v_mov_b32_e32 v45, 0
	v_mov_b32_e32 v46, 0
	v_mov_b32_e32 v47, 0
	v_mov_b32_e32 v48, 0
	v_mov_b32_e32 v49, 0
	v_mov_b32_e32 v50, 0
	v_mov_b32_e32 v51, 0
	v_mov_b32_e32 v52, 0
	v_mov_b32_e32 v53, 0
	v_mov_b32_e32 v54, 0
	v_mov_b32_e32 v55, 0
	v_mov_b32_e32 v56, 0
	v_mov_b32_e32 v57, 0
	v_mov_b32_e32 v58, 0
	v_mov_b32_e32 v59, 0
	v_mov_b32_e32 v60, 0
	v_mov_b32_e32 v61, 0
	v_mov_b32_e32 v62, 0
	v_mov_b32_e32 v63, 0
	v_mov_b32_e32 v64, 0
	v_mov_b32_e32 v65, 0
	v_mov_b32_e32 v66, 0
	v_mov_b32_e32 v67, 0
	v_mov_b32_e32 v68, 0
	v_mov_b32_e32 v69, 0
	v_mov_b32_e32 v70, 0
	v_mov_b32_e32 v71, 0
	v_mov_b32_e32 v72, 0
	v_mov_b32_e32 v73, 0
	v_mov_b32_e32 v74, 0
	v_mov_b32_e32 v75, 0
	v_mov_b32_e32 v76, 0
	v_mov_b32_e32 v77, 0
	v_mov_b32_e32 v78, 0
	v_mov_b32_e32 v79, 0
	v_mov_b32_e32 v80, 0
	v_mov_b32_e32 v81, 0
	v_mov_b32_e32 v82, 0
	v_mov_b32_e32 v83, 0
	v_mov_b32_e32 v84, 0
	v_mov_b32_e32 v85, 0
	v_mov_b32_e32 v86, 0
	v_mov_b32_e32 v87, 0
	v_mov_b32_e32 v88, 0
	v_mov_b32_e32 v89, 0
	v_mov_b32_e32 v90, 0
	v_mov_b32_e32 v91, 0
	v_mov_b32_e32 v92, 0
	v_mov_b32_e32 v93, 0
	v_mov_b32_e32 v94, 0
	v_mov_b32_e32 v95, 0
	v_mov_b32_e32 v96, 0
	v_mov_b32_e32 v97, 0
	v_mov_b32_e32 v98, 0
	v_mov_b32_e32 v99, 0
	v_mov_b32_e32 v100, 0
	v_mov_b32_e32 v101, 0
	v_mov_b32_e32 v102, 0
	v_mov_b32_e32 v103, 0
	v_mov_b32_e32 v104, 0
	v_mov_b32_e32 v105, 0
	v_mov_b32_e32 v106, 0
	v_mov_b32_e32 v107, 0
	v_mov_b32_e32 v108, 0
	v_mov_b32_e32 v109, 0
	v_mov_b32_e32 v110, 0
	v_mov_b32_e32 v111, 0
	v_mov_b32_e32 v112, 0
	v_mov_b32_e32 v113, 0
	v_mov_b32_e32 v114, 0
	v_mov_b32_e32 v115, 0
	v_mov_b32_e32 v116, 0
	v_mov_b32_e32 v117, 0
	v_mov_b32_e32 v118, 0
	v_mov_b32_e32 v119, 0
	v_mov_b32_e32 v120, 0
	v_mov_b32_e32 v121, 0
	v_mov_b32_e32 v122, 0
	v_mov_b32_e32 v123, 0
	v_mov_b32_e32 v124, 0
	v_mov_b32_e32 v125, 0
	v_mov_b32_e32 v126, 0
	v_mov_b32_e32 v127, 0
	v_mov_b32_e32 v128, 0
	v_mov_b32_e32 v129, 0
	s_setprio 0
	s_waitcnt vmcnt(12)
	s_barrier
	ds_read_b128 v[146:149], v136 offset:0
	ds_read_b128 v[152:155], v136 offset:1024
	ds_read_b128 v[156:159], v136 offset:2048
	ds_read_b128 v[162:165], v136 offset:3072
	ds_read_b128 v[166:169], v136 offset:4096
	ds_read_b128 v[170:173], v136 offset:5120
	ds_read_b128 v[176:179], v136 offset:6144
	ds_read_b128 v[180:183], v136 offset:7168
	ds_read_b128 v[184:187], v137 offset:16384
	ds_read_b128 v[188:191], v137 offset:17408
	ds_read_b128 v[192:195], v137 offset:18432
	ds_read_b128 v[196:199], v137 offset:19456
	s_movk_i32 s1, 0x6000
	s_mov_b32 s12, 0
	.p2align 3
	s_waitcnt vmcnt(6) lgkmcnt(0)
	s_barrier
	s_setprio 2
	v_add_u32_e32 v144, s1, v136
	v_mfma_f32_16x16x32_bf16 v[126:129], v[184:187], v[146:149], v[126:129]
	ds_read_b128 v[200:203], v144 offset:0
	v_mfma_f32_16x16x32_bf16 v[122:125], v[184:187], v[152:155], v[122:125]
	ds_read_b128 v[204:207], v144 offset:1024
	v_mfma_f32_16x16x32_bf16 v[118:121], v[184:187], v[156:159], v[118:121]
	ds_read_b128 v[208:211], v144 offset:2048
	v_mfma_f32_16x16x32_bf16 v[114:117], v[184:187], v[162:165], v[114:117]
	ds_read_b128 v[212:215], v144 offset:3072
	v_mfma_f32_16x16x32_bf16 v[110:113], v[184:187], v[166:169], v[110:113]
	ds_read_b128 v[216:219], v144 offset:4096
	v_mfma_f32_16x16x32_bf16 v[106:109], v[184:187], v[170:173], v[106:109]
	ds_read_b128 v[220:223], v144 offset:5120
	v_mfma_f32_16x16x32_bf16 v[102:105], v[184:187], v[176:179], v[102:105]
	ds_read_b128 v[224:227], v144 offset:6144
	v_mfma_f32_16x16x32_bf16 v[98:101], v[184:187], v[180:183], v[98:101]
	ds_read_b128 v[228:231], v144 offset:7168
	v_mfma_f32_16x16x32_bf16 v[94:97], v[188:191], v[146:149], v[94:97]
	v_add_u32_e64 v144, s1, v137
	v_mfma_f32_16x16x32_bf16 v[90:93], v[188:191], v[152:155], v[90:93]
	v_mfma_f32_16x16x32_bf16 v[86:89], v[188:191], v[156:159], v[86:89]
	ds_read_b128 v[232:235], v144 offset:16384
	v_mfma_f32_16x16x32_bf16 v[82:85], v[188:191], v[162:165], v[82:85]
	ds_read_b128 v[236:239], v144 offset:17408
	v_mfma_f32_16x16x32_bf16 v[78:81], v[188:191], v[166:169], v[78:81]
	ds_read_b128 v[240:243], v144 offset:18432
	v_mfma_f32_16x16x32_bf16 v[74:77], v[188:191], v[170:173], v[74:77]
	ds_read_b128 v[244:247], v144 offset:19456
	v_mfma_f32_16x16x32_bf16 v[70:73], v[188:191], v[176:179], v[70:73]
	s_add_i32 s13, s98, s12
	s_mov_b32 m0, s13
	v_lshl_add_u64 v[142:143], v[132:133], 0, s[2:3]
	v_mfma_f32_16x16x32_bf16 v[66:69], v[188:191], v[180:183], v[66:69]
	global_load_lds_dwordx4 v[132:133], off
	s_add_i32 m0, m0, 0x1000
	v_mfma_f32_16x16x32_bf16 v[62:65], v[192:195], v[146:149], v[62:65]
	v_mfma_f32_16x16x32_bf16 v[58:61], v[192:195], v[152:155], v[58:61]
	v_mfma_f32_16x16x32_bf16 v[54:57], v[192:195], v[156:159], v[54:57]
	global_load_lds_dwordx4 v[142:143], off
	v_lshl_add_u64 v[142:143], v[142:143], 0, s[2:3]
	s_add_i32 m0, m0, 0x1000
	v_mfma_f32_16x16x32_bf16 v[50:53], v[192:195], v[162:165], v[50:53]
	v_mfma_f32_16x16x32_bf16 v[46:49], v[192:195], v[166:169], v[46:49]
	v_mfma_f32_16x16x32_bf16 v[42:45], v[192:195], v[170:173], v[42:45]
	global_load_lds_dwordx4 v[142:143], off
	v_lshl_add_u64 v[142:143], v[142:143], 0, s[2:3]
	s_add_i32 m0, m0, 0x1000
	v_mfma_f32_16x16x32_bf16 v[38:41], v[192:195], v[176:179], v[38:41]
	v_mfma_f32_16x16x32_bf16 v[34:37], v[192:195], v[180:183], v[34:37]
	s_setprio 0
	s_nop 0
	v_mfma_f32_16x16x32_bf16 v[30:33], v[196:199], v[146:149], v[30:33]
	global_load_lds_dwordx4 v[142:143], off
	s_add_i32 m0, m0, 0x1000
	v_lshl_add_u64 v[142:143], v[134:135], 0, s[2:3]
	v_mfma_f32_16x16x32_bf16 v[26:29], v[196:199], v[152:155], v[26:29]
	v_mfma_f32_16x16x32_bf16 v[22:25], v[196:199], v[156:159], v[22:25]
	v_mfma_f32_16x16x32_bf16 v[18:21], v[196:199], v[162:165], v[18:21]
	global_load_lds_dwordx4 v[134:135], off
	s_add_i32 m0, m0, 0x1000
	v_lshl_add_u64 v[132:133], v[132:133], 0, s[10:11]
	v_mfma_f32_16x16x32_bf16 v[14:17], v[196:199], v[166:169], v[14:17]
	v_mfma_f32_16x16x32_bf16 v[10:13], v[196:199], v[170:173], v[10:13]
	v_mfma_f32_16x16x32_bf16 v[6:9], v[196:199], v[176:179], v[6:9]
	global_load_lds_dwordx4 v[142:143], off
	v_lshl_add_u64 v[134:135], v[134:135], 0, s[4:5]
	v_mfma_f32_16x16x32_bf16 v[2:5], v[196:199], v[180:183], v[2:5]
	s_mov_b32 s12, s1
	s_nop 0
	s_add_i32 s1, s1, 0x6000
	s_cmp_eq_u32 s1, 0x12000
	s_cselect_b32 s1, 0, s1
	s_nop 0
	.p2align 3
	s_waitcnt vmcnt(6) lgkmcnt(0)
	s_barrier
;     ...
;   for (int kt = 0; kt < nk; kt++) {
;     if (kt + 1 < nk) asm volatile("s_waitcnt vmcnt(6)" ::: "memory");
;     else asm volatile("s_waitcnt vmcnt(0)" ::: "memory");
;     __builtin_amdgcn_s_barrier();
;     asm volatile("" ::: "memory");
;     if (kt + 2 < nk) G2_STAGE(kt + 2);
;     const char* cS = smem + (kt % 3) * 24576;
;     bf16x8 xa[8], wb[4];
; #pragma unroll
;     for (int f = 0; f < 8; f++) xa[f] = *(const bf16x8*)(cS + aoff + f * 1024);
; #pragma unroll
;     for (int f = 0; f < 4; f++) wb[f] = *(const bf16x8*)(cS + boff + f * 1024);
; #pragma unroll
;     for (int nf = 0; nf < 4; nf++)
; #pragma unroll
;       for (int mf = 0; mf < 8; mf++)
;         acc[nf][mf] = __builtin_amdgcn_mfma_f32_16x16x32_bf16(wb[nf], xa[mf], acc[nf][mf], 0, 0, 0);
	s_setprio 2
	v_add_u32_e32 v144, s1, v136
	v_mfma_f32_16x16x32_bf16 v[126:129], v[232:235], v[200:203], v[126:129]
	ds_read_b128 v[146:149], v144 offset:0
	v_mfma_f32_16x16x32_bf16 v[122:125], v[232:235], v[204:207], v[122:125]
	ds_read_b128 v[152:155], v144 offset:1024
	v_mfma_f32_16x16x32_bf16 v[118:121], v[232:235], v[208:211], v[118:121]
	ds_read_b128 v[156:159], v144 offset:2048
	v_mfma_f32_16x16x32_bf16 v[114:117], v[232:235], v[212:215], v[114:117]
	ds_read_b128 v[162:165], v144 offset:3072
	v_mfma_f32_16x16x32_bf16 v[110:113], v[232:235], v[216:219], v[110:113]
	ds_read_b128 v[166:169], v144 offset:4096
	v_mfma_f32_16x16x32_bf16 v[106:109], v[232:235], v[220:223], v[106:109]
	ds_read_b128 v[170:173], v144 offset:5120
	v_mfma_f32_16x16x32_bf16 v[102:105], v[232:235], v[224:227], v[102:105]
	ds_read_b128 v[176:179], v144 offset:6144
	v_mfma_f32_16x16x32_bf16 v[98:101], v[232:235], v[228:231], v[98:101]
	ds_read_b128 v[180:183], v144 offset:7168
	v_mfma_f32_16x16x32_bf16 v[94:97], v[236:239], v[200:203], v[94:97]
	v_add_u32_e64 v144, s1, v137
	v_mfma_f32_16x16x32_bf16 v[90:93], v[236:239], v[204:207], v[90:93]
	v_mfma_f32_16x16x32_bf16 v[86:89], v[236:239], v[208:211], v[86:89]
	ds_read_b128 v[184:187], v144 offset:16384
	v_mfma_f32_16x16x32_bf16 v[82:85], v[236:239], v[212:215], v[82:85]
	ds_read_b128 v[188:191], v144 offset:17408
	v_mfma_f32_16x16x32_bf16 v[78:81], v[236:239], v[216:219], v[78:81]
	ds_read_b128 v[192:195], v144 offset:18432
	v_mfma_f32_16x16x32_bf16 v[74:77], v[236:239], v[220:223], v[74:77]
	ds_read_b128 v[196:199], v144 offset:19456
	v_mfma_f32_16x16x32_bf16 v[70:73], v[236:239], v[224:227], v[70:73]
	v_mfma_f32_16x16x32_bf16 v[66:69], v[236:239], v[228:231], v[66:69]
	v_mfma_f32_16x16x32_bf16 v[62:65], v[240:243], v[200:203], v[62:65]
	v_mfma_f32_16x16x32_bf16 v[58:61], v[240:243], v[204:207], v[58:61]
	v_mfma_f32_16x16x32_bf16 v[54:57], v[240:243], v[208:211], v[54:57]
	v_mfma_f32_16x16x32_bf16 v[50:53], v[240:243], v[212:215], v[50:53]
	v_mfma_f32_16x16x32_bf16 v[46:49], v[240:243], v[216:219], v[46:49]
	v_mfma_f32_16x16x32_bf16 v[42:45], v[240:243], v[220:223], v[42:45]
	v_mfma_f32_16x16x32_bf16 v[38:41], v[240:243], v[224:227], v[38:41]
	v_mfma_f32_16x16x32_bf16 v[34:37], v[240:243], v[228:231], v[34:37]
	s_setprio 0
	s_nop 0
	v_mfma_f32_16x16x32_bf16 v[30:33], v[244:247], v[200:203], v[30:33]
	v_mfma_f32_16x16x32_bf16 v[26:29], v[244:247], v[204:207], v[26:29]
	v_mfma_f32_16x16x32_bf16 v[22:25], v[244:247], v[208:211], v[22:25]
	v_mfma_f32_16x16x32_bf16 v[18:21], v[244:247], v[212:215], v[18:21]
	v_mfma_f32_16x16x32_bf16 v[14:17], v[244:247], v[216:219], v[14:17]
	v_mfma_f32_16x16x32_bf16 v[10:13], v[244:247], v[220:223], v[10:13]
	v_mfma_f32_16x16x32_bf16 v[6:9], v[244:247], v[224:227], v[6:9]
	v_mfma_f32_16x16x32_bf16 v[2:5], v[244:247], v[228:231], v[2:5]
	s_mov_b32 s12, s1
	s_nop 0
	s_add_i32 s1, s1, 0x6000
	s_cmp_eq_u32 s1, 0x12000
	s_cselect_b32 s1, 0, s1
	s_nop 0
	.p2align 3
	s_waitcnt vmcnt(0) lgkmcnt(0)
	s_barrier
	s_setprio 2
	v_add_u32_e32 v144, s1, v136
	v_mfma_f32_16x16x32_bf16 v[126:129], v[184:187], v[146:149], v[126:129]
	ds_read_b128 v[200:203], v144 offset:0
	v_mfma_f32_16x16x32_bf16 v[122:125], v[184:187], v[152:155], v[122:125]
	ds_read_b128 v[204:207], v144 offset:1024
	v_mfma_f32_16x16x32_bf16 v[118:121], v[184:187], v[156:159], v[118:121]
	ds_read_b128 v[208:211], v144 offset:2048
	v_mfma_f32_16x16x32_bf16 v[114:117], v[184:187], v[162:165], v[114:117]
	ds_read_b128 v[212:215], v144 offset:3072
	v_mfma_f32_16x16x32_bf16 v[110:113], v[184:187], v[166:169], v[110:113]
	ds_read_b128 v[216:219], v144 offset:4096
	v_mfma_f32_16x16x32_bf16 v[106:109], v[184:187], v[170:173], v[106:109]
	ds_read_b128 v[220:223], v144 offset:5120
	v_mfma_f32_16x16x32_bf16 v[102:105], v[184:187], v[176:179], v[102:105]
	ds_read_b128 v[224:227], v144 offset:6144
	v_mfma_f32_16x16x32_bf16 v[98:101], v[184:187], v[180:183], v[98:101]
	ds_read_b128 v[228:231], v144 offset:7168
	v_mfma_f32_16x16x32_bf16 v[94:97], v[188:191], v[146:149], v[94:97]
	v_add_u32_e64 v144, s1, v137
	v_mfma_f32_16x16x32_bf16 v[90:93], v[188:191], v[152:155], v[90:93]
	v_mfma_f32_16x16x32_bf16 v[86:89], v[188:191], v[156:159], v[86:89]
	ds_read_b128 v[232:235], v144 offset:16384
	v_mfma_f32_16x16x32_bf16 v[82:85], v[188:191], v[162:165], v[82:85]
	ds_read_b128 v[236:239], v144 offset:17408
	v_mfma_f32_16x16x32_bf16 v[78:81], v[188:191], v[166:169], v[78:81]
	ds_read_b128 v[240:243], v144 offset:18432
	v_mfma_f32_16x16x32_bf16 v[74:77], v[188:191], v[170:173], v[74:77]
	ds_read_b128 v[244:247], v144 offset:19456
	v_mfma_f32_16x16x32_bf16 v[70:73], v[188:191], v[176:179], v[70:73]
	v_mfma_f32_16x16x32_bf16 v[66:69], v[188:191], v[180:183], v[66:69]
	v_mfma_f32_16x16x32_bf16 v[62:65], v[192:195], v[146:149], v[62:65]
	v_mfma_f32_16x16x32_bf16 v[58:61], v[192:195], v[152:155], v[58:61]
	v_mfma_f32_16x16x32_bf16 v[54:57], v[192:195], v[156:159], v[54:57]
	v_mfma_f32_16x16x32_bf16 v[50:53], v[192:195], v[162:165], v[50:53]
	v_mfma_f32_16x16x32_bf16 v[46:49], v[192:195], v[166:169], v[46:49]
	v_mfma_f32_16x16x32_bf16 v[42:45], v[192:195], v[170:173], v[42:45]
	v_mfma_f32_16x16x32_bf16 v[38:41], v[192:195], v[176:179], v[38:41]
	v_mfma_f32_16x16x32_bf16 v[34:37], v[192:195], v[180:183], v[34:37]
	s_setprio 0
	s_nop 0
	v_mfma_f32_16x16x32_bf16 v[30:33], v[196:199], v[146:149], v[30:33]
	v_mfma_f32_16x16x32_bf16 v[26:29], v[196:199], v[152:155], v[26:29]
	v_mfma_f32_16x16x32_bf16 v[22:25], v[196:199], v[156:159], v[22:25]
	v_mfma_f32_16x16x32_bf16 v[18:21], v[196:199], v[162:165], v[18:21]
	v_mfma_f32_16x16x32_bf16 v[14:17], v[196:199], v[166:169], v[14:17]
	v_mfma_f32_16x16x32_bf16 v[10:13], v[196:199], v[170:173], v[10:13]
	v_mfma_f32_16x16x32_bf16 v[6:9], v[196:199], v[176:179], v[6:9]
	v_mfma_f32_16x16x32_bf16 v[2:5], v[196:199], v[180:183], v[2:5]
	s_mov_b32 s12, s1
	s_nop 0
	s_add_i32 s1, s1, 0x6000
	s_cmp_eq_u32 s1, 0x12000
	s_cselect_b32 s1, 0, s1
	s_nop 0
	s_mov_b32 s4, 0x8000
	s_mov_b32 s5, 0
	s_mov_b32 s8, 0x10000
	s_mov_b32 s9, 0
	s_mov_b32 s40, 0x3fd744fd
	.p2align 3
	s_waitcnt lgkmcnt(0)
; DEVI float blo(unsigned u) { return __uint_as_float(u << 16); }
; DEVI float bhi(unsigned u) { return __uint_as_float(u & 0xffff0000u); }
;     ...
;     for (int nf = 0; nf < 4; nf++)
; #pragma unroll
;       for (int mf = 0; mf < 8; mf++)
;         acc[nf][mf] = __builtin_amdgcn_mfma_f32_16x16x32_bf16(wb[nf], xa[mf], acc[nf][mf], 0, 0, 0);
;     ...
; #pragma unroll
;       for (int nf = 0; nf < 4; nf++) {
;         const int col = n0 + wn * 64 + nf * 16 + quad * 4;
;         f32x4 a = acc[nf][mf];
;         if (EPI == EPI_RESID || EPI == EPI_RESID_ATOMIC) {
;           f32x4 x = a;
;           if (EPI == EPI_RESID || kpart == 0) {
;             const u32x2 xr = *(const u32x2*)((const u16*)(p.ws + WS_XB) + (size_t)row * 1024 + col);
;             x[0] += ALPHA * blo(xr[0]); x[1] += ALPHA * bhi(xr[0]); x[2] += ALPHA * blo(xr[1]); x[3] += ALPHA * bhi(xr[1]);
;           }
;           if (EPI == EPI_RESID) *(f32x4*)((float*)(p.ws + WS_XF) + (size_t)row * 1024 + col) = x;
;           else *(f32x4*)((float*)(p.ws + WS_SLAB) + ((size_t)kpart * 512 + (row - T_P)) * 1024 + col) = x;
	s_nop 0
	v_mfma_f32_16x16x32_bf16 v[126:129], v[232:235], v[200:203], v[126:129]
	v_mfma_f32_16x16x32_bf16 v[122:125], v[232:235], v[204:207], v[122:125]
	v_mfma_f32_16x16x32_bf16 v[118:121], v[232:235], v[208:211], v[118:121]
	v_mfma_f32_16x16x32_bf16 v[114:117], v[232:235], v[212:215], v[114:117]
	v_mfma_f32_16x16x32_bf16 v[110:113], v[232:235], v[216:219], v[110:113]
	v_mfma_f32_16x16x32_bf16 v[106:109], v[232:235], v[220:223], v[106:109]
	v_mfma_f32_16x16x32_bf16 v[102:105], v[232:235], v[224:227], v[102:105]
	v_mfma_f32_16x16x32_bf16 v[98:101], v[232:235], v[228:231], v[98:101]
	v_mfma_f32_16x16x32_bf16 v[94:97], v[236:239], v[200:203], v[94:97]
	v_mfma_f32_16x16x32_bf16 v[90:93], v[236:239], v[204:207], v[90:93]
	v_mfma_f32_16x16x32_bf16 v[86:89], v[236:239], v[208:211], v[86:89]
	v_mfma_f32_16x16x32_bf16 v[82:85], v[236:239], v[212:215], v[82:85]
	v_mfma_f32_16x16x32_bf16 v[78:81], v[236:239], v[216:219], v[78:81]
	v_mfma_f32_16x16x32_bf16 v[74:77], v[236:239], v[220:223], v[74:77]
	v_mfma_f32_16x16x32_bf16 v[70:73], v[236:239], v[224:227], v[70:73]
	v_mfma_f32_16x16x32_bf16 v[66:69], v[236:239], v[228:231], v[66:69]
	v_mfma_f32_16x16x32_bf16 v[62:65], v[240:243], v[200:203], v[62:65]
	v_mfma_f32_16x16x32_bf16 v[58:61], v[240:243], v[204:207], v[58:61]
	v_mfma_f32_16x16x32_bf16 v[54:57], v[240:243], v[208:211], v[54:57]
	v_mfma_f32_16x16x32_bf16 v[50:53], v[240:243], v[212:215], v[50:53]
	v_mfma_f32_16x16x32_bf16 v[46:49], v[240:243], v[216:219], v[46:49]
	v_mfma_f32_16x16x32_bf16 v[42:45], v[240:243], v[220:223], v[42:45]
	v_mfma_f32_16x16x32_bf16 v[38:41], v[240:243], v[224:227], v[38:41]
	v_mfma_f32_16x16x32_bf16 v[34:37], v[240:243], v[228:231], v[34:37]
	v_mfma_f32_16x16x32_bf16 v[30:33], v[244:247], v[200:203], v[30:33]
	v_mfma_f32_16x16x32_bf16 v[26:29], v[244:247], v[204:207], v[26:29]
	v_mfma_f32_16x16x32_bf16 v[22:25], v[244:247], v[208:211], v[22:25]
	v_mfma_f32_16x16x32_bf16 v[18:21], v[244:247], v[212:215], v[18:21]
	v_mfma_f32_16x16x32_bf16 v[14:17], v[244:247], v[216:219], v[14:17]
	v_mfma_f32_16x16x32_bf16 v[10:13], v[244:247], v[220:223], v[10:13]
	v_mfma_f32_16x16x32_bf16 v[6:9], v[244:247], v[224:227], v[6:9]
	v_mfma_f32_16x16x32_bf16 v[2:5], v[244:247], v[228:231], v[2:5]
	s_mov_b32 m0, s39
	s_cmp_eq_u32 s99, 0
	s_cbranch_scc1 .Lta8_first
	s_nop 7
	global_store_dwordx4 v[140:141], v[126:129], off offset:0
	global_store_dwordx4 v[140:141], v[94:97], off offset:64
	global_store_dwordx4 v[140:141], v[62:65], off offset:128
	global_store_dwordx4 v[140:141], v[30:33], off offset:192
	v_lshl_add_u64 v[140:141], v[140:141], 0, s[8:9]
	global_store_dwordx4 v[140:141], v[122:125], off offset:0
	global_store_dwordx4 v[140:141], v[90:93], off offset:64
	global_store_dwordx4 v[140:141], v[58:61], off offset:128
	global_store_dwordx4 v[140:141], v[26:29], off offset:192
	v_lshl_add_u64 v[140:141], v[140:141], 0, s[8:9]
	global_store_dwordx4 v[140:141], v[118:121], off offset:0
	global_store_dwordx4 v[140:141], v[86:89], off offset:64
	global_store_dwordx4 v[140:141], v[54:57], off offset:128
	global_store_dwordx4 v[140:141], v[22:25], off offset:192
	v_lshl_add_u64 v[140:141], v[140:141], 0, s[8:9]
	global_store_dwordx4 v[140:141], v[114:117], off offset:0
	global_store_dwordx4 v[140:141], v[82:85], off offset:64
	global_store_dwordx4 v[140:141], v[50:53], off offset:128
	global_store_dwordx4 v[140:141], v[18:21], off offset:192
	v_lshl_add_u64 v[140:141], v[140:141], 0, s[8:9]
	global_store_dwordx4 v[140:141], v[110:113], off offset:0
	global_store_dwordx4 v[140:141], v[78:81], off offset:64
	global_store_dwordx4 v[140:141], v[46:49], off offset:128
	global_store_dwordx4 v[140:141], v[14:17], off offset:192
	v_lshl_add_u64 v[140:141], v[140:141], 0, s[8:9]
	global_store_dwordx4 v[140:141], v[106:109], off offset:0
	global_store_dwordx4 v[140:141], v[74:77], off offset:64
	global_store_dwordx4 v[140:141], v[42:45], off offset:128
	global_store_dwordx4 v[140:141], v[10:13], off offset:192
	v_lshl_add_u64 v[140:141], v[140:141], 0, s[8:9]
	global_store_dwordx4 v[140:141], v[102:105], off offset:0
	global_store_dwordx4 v[140:141], v[70:73], off offset:64
	global_store_dwordx4 v[140:141], v[38:41], off offset:128
	global_store_dwordx4 v[140:141], v[6:9], off offset:192
	v_lshl_add_u64 v[140:141], v[140:141], 0, s[8:9]
	global_store_dwordx4 v[140:141], v[98:101], off offset:0
	global_store_dwordx4 v[140:141], v[66:69], off offset:64
	global_store_dwordx4 v[140:141], v[34:37], off offset:128
	global_store_dwordx4 v[140:141], v[2:5], off offset:192
	v_readlane_b32 s0, v250, 7
	s_cmpk_lg_u32 s0, 0x200
	s_cbranch_scc1 .Lta8_ar1
	s_mov_b32 s0, 1
	v_writelane_b32 v255, s0, 41
	v_readlane_b32 s1, v250, 0
	s_lshr_b32 s12, s1, 3
	s_and_b32 s1, s1, 7
	s_lshl_b32 s1, s1, 6
	s_add_i32 s1, s1, s12
	s_sub_i32 s38, s1, 0x200

; #define LAS __attribute__((address_space(3)))
;     ...
;   const int nk = (nk_part < 0) ? (K >> 5) : nk_part;
;   const int lrow = tid >> 2, lpc = tid & 3;
;   const int lch = lpc ^ ((0x78 >> (((lrow >> 2) & 3) * 2)) & 3);
;   const u16* ga = A + (size_t)(m0 + lrow) * lda + kbeg + lch * 8;
;   const u16* gb = Bt + (size_t)(n0 + lrow) * K + kbeg + lch * 8;
;   const size_t ga1 = (size_t)64 * lda, gb1 = (size_t)64 * K;
;   const unsigned lds0 = (unsigned)(uintptr_t)(LAS char*)smem + (unsigned)__builtin_amdgcn_readfirstlane(wid) * 1024u;
;     ...
;   __syncthreads();
;   G2_STAGE(0); G2_STAGE(1);
; DEVI void run_phase(const Params& p, int ph, char* smem) {
;     ...
;           const int u_ = t - 512, tl_ = u_ / 8, q_ = u_ - tl_ * 8;
;           gemm_tile256<EPI_RESID_ATOMIC>(p, mix, 1024, Bt, 1024, (64 + (tl_ & 1)) * 256, (tl_ >> 1) * 128, nullptr, 0, smem, q_ * 128, 4, q_);
.LBB0_758:
	s_cmpk_gt_i32 s39, 0x1ff
	s_mov_b64 s[2:3], -1
	s_cbranch_scc0 .LBB0_812
	s_setprio 2
	s_sub_i32 s43, s39, 512
	s_lshr_b32 s42, s43, 3
	s_and_b32 s98, s43, 7
	s_lshr_b32 s15, s42, 1
	s_and_b32 s42, s42, 1
	s_add_i32 s42, s42, 64
	v_readlane_b32 s2, v250, 5
	v_readlane_b32 s3, v250, 6
	v_readlane_b32 s43, v254, 62
	s_mul_i32 s1, s42, 0x80000
	s_add_u32 s4, s2, s1
	s_addc_u32 s5, s3, 0
	s_add_u32 s4, s4, 0xb580000
	s_addc_u32 s5, s5, 0
	s_mul_i32 s1, s43, 0x200000
	s_mul_i32 s14, s15, 0x40000
	s_add_i32 s1, s1, s14
	s_add_u32 s10, s2, s1
	s_addc_u32 s11, s3, 0
	s_add_u32 s10, s10, 0x15e00000
	s_addc_u32 s11, s11, 0
	s_mul_i32 s1, s98, 256
	s_add_u32 s4, s4, s1
	s_addc_u32 s5, s5, 0
	s_mul_i32 s1, s98, 512
	s_add_u32 s10, s10, s1
	s_addc_u32 s11, s11, 0
	s_movk_i32 s0, 0x78
	v_lshrrev_b32_e32 v0, 2, v145
	v_and_b32_e32 v131, 3, v145
	v_bfe_u32 v136, v145, 4, 2
	v_lshlrev_b32_e32 v136, 1, v136
	v_lshrrev_b32_e64 v136, v136, s0
	v_and_b32_e32 v136, 3, v136
	v_xor_b32_e32 v131, v131, v136
	v_lshlrev_b32_e32 v131, 4, v131
	s_movk_i32 s14, 0x800
	v_mad_u32_u24 v0, v0, s14, v131
	v_bfe_u32 v137, v145, 2, 1
	s_movk_i32 s14, 0x7c0
	v_mul_u32_u24_e32 v136, s14, v137
	v_sub_u32_e32 v136, v0, v136
	v_mov_b32_e32 v137, 0
	v_lshl_add_u64 v[134:135], s[10:11], 0, v[136:137]
	v_bfe_u32 v137, v145, 2, 1
	s_mov_b32 s12, 64
	s_mov_b32 s13, 0
	v_lshl_add_u64 v[132:133], s[4:5], 0, v[0:1]
	v_bfe_u32 v136, v145, 2, 2
	v_lshlrev_b32_e32 v136, 1, v136
	v_lshrrev_b32_e64 v136, v136, s0
	v_and_b32_e32 v136, 3, v136
	v_bfe_u32 v137, v145, 4, 2
	v_xor_b32_e32 v136, v136, v137
	v_lshlrev_b32_e32 v136, 4, v136
	v_and_b32_e32 v131, 15, v145
	v_lshl_or_b32 v136, v131, 6, v136
	v_bfe_u32 v137, v145, 6, 1
	v_lshl_or_b32 v137, v137, 12, v136
	v_lshrrev_b32_e32 v0, 7, v145
	v_lshl_or_b32 v136, v0, 13, v136
	v_and_b32_e32 v140, 1, v131
	v_lshl_or_b32 v131, v0, 7, v131
	v_bfe_u32 v0, v145, 4, 2
	v_lshlrev_b32_e32 v0, 3, v0
	v_bfe_u32 v141, v145, 6, 1
	s_lshl_b32 s1, s42, 19
	s_lshl_b32 s14, s15, 8
	s_add_i32 s1, s1, s14
	s_add_u32 s4, s2, s1
	s_addc_u32 s5, s3, 0
	s_add_u32 s4, s4, 0x4200000
	s_addc_u32 s5, s5, 0
	v_lshlrev_b32_e32 v138, 11, v131
	v_lshl_add_u32 v138, v141, 7, v138
	v_bfe_u32 v139, v145, 4, 1
	v_lshl_add_u32 v138, v139, 5, v138
	v_bfe_u32 v139, v145, 5, 1
	v_lshl_add_u32 v138, v139, 4, v138
	v_mov_b32_e32 v139, 0
	v_lshl_add_u64 v[138:139], s[4:5], 0, v[138:139]
	s_and_b32 s1, s42, 1
	s_lshl_b32 s1, s1, 20
	s_lshl_b32 s14, s98, 21
	s_add_i32 s1, s1, s14
	s_lshl_b32 s14, s15, 9
	s_add_i32 s1, s1, s14
	s_add_u32 s10, s2, s1
	s_addc_u32 s11, s3, 0
	s_add_u32 s10, s10, 0x1dcc0000
	s_addc_u32 s11, s11, 0
	v_lshlrev_b32_e32 v140, 12, v131
	v_lshl_add_u32 v140, v141, 8, v140
	v_lshl_add_u32 v140, v0, 1, v140
	v_mov_b32_e32 v141, 0
	v_lshl_add_u64 v[140:141], s[10:11], 0, v[140:141]
	s_mov_b32 s2, 0x20000
	s_mov_b32 s3, 0
	v_lshrrev_b32_e32 v0, 6, v145
	v_lshlrev_b32_e32 v0, 10, v0
	s_nop 0
	v_readfirstlane_b32 s43, v0
	s_mov_b32 s40, m0
	s_mov_b32 s4, 128
	s_mov_b32 s5, 0
	s_barrier
	s_add_i32 s15, s43, 0x0
	s_mov_b32 m0, s15
	v_lshl_add_u64 v[142:143], v[132:133], 0, s[2:3]
	global_load_lds_dwordx4 v[132:133], off
	s_add_i32 m0, m0, 0x1000
	s_nop 0
	global_load_lds_dwordx4 v[142:143], off
	v_lshl_add_u64 v[142:143], v[142:143], 0, s[2:3]
	s_add_i32 m0, m0, 0x1000
	s_nop 0
	global_load_lds_dwordx4 v[142:143], off
	v_lshl_add_u64 v[142:143], v[142:143], 0, s[2:3]
	s_add_i32 m0, m0, 0x1000
	s_nop 0
	global_load_lds_dwordx4 v[142:143], off
	s_add_i32 m0, m0, 0x1000
	v_lshl_add_u64 v[142:143], v[134:135], 0, s[2:3]
	s_nop 0
	global_load_lds_dwordx4 v[134:135], off
	s_add_i32 m0, m0, 0x1000
	v_lshl_add_u64 v[132:133], v[132:133], 0, s[12:13]
	s_nop 0
	global_load_lds_dwordx4 v[142:143], off
	v_lshl_add_u64 v[134:135], v[134:135], 0, s[4:5]
	s_nop 0
	s_add_i32 s15, s43, 0x6000
	s_mov_b32 m0, s15
	v_lshl_add_u64 v[142:143], v[132:133], 0, s[2:3]
	global_load_lds_dwordx4 v[132:133], off
	s_add_i32 m0, m0, 0x1000
	s_nop 0
	global_load_lds_dwordx4 v[142:143], off
	v_lshl_add_u64 v[142:143], v[142:143], 0, s[2:3]
	s_add_i32 m0, m0, 0x1000
	s_nop 0
	global_load_lds_dwordx4 v[142:143], off
	v_lshl_add_u64 v[142:143], v[142:143], 0, s[2:3]
	s_add_i32 m0, m0, 0x1000
	s_nop 0
	global_load_lds_dwordx4 v[142:143], off
	s_add_i32 m0, m0, 0x1000
	v_lshl_add_u64 v[142:143], v[134:135], 0, s[2:3]
	s_nop 0
	global_load_lds_dwordx4 v[134:135], off
	s_add_i32 m0, m0, 0x1000
	v_lshl_add_u64 v[132:133], v[132:133], 0, s[12:13]
	s_nop 0
	global_load_lds_dwordx4 v[142:143], off
	v_lshl_add_u64 v[134:135], v[134:135], 0, s[4:5]
	s_nop 0
	s_add_i32 s15, s43, 0xc000
	s_mov_b32 m0, s15
	v_lshl_add_u64 v[142:143], v[132:133], 0, s[2:3]
	global_load_lds_dwordx4 v[132:133], off
	s_add_i32 m0, m0, 0x1000
	s_nop 0
	global_load_lds_dwordx4 v[142:143], off
	v_lshl_add_u64 v[142:143], v[142:143], 0, s[2:3]
	s_add_i32 m0, m0, 0x1000
	s_nop 0
	global_load_lds_dwordx4 v[142:143], off
	v_lshl_add_u64 v[142:143], v[142:143], 0, s[2:3]
	s_add_i32 m0, m0, 0x1000
	s_nop 0
	global_load_lds_dwordx4 v[142:143], off
	s_add_i32 m0, m0, 0x1000
	v_lshl_add_u64 v[142:143], v[134:135], 0, s[2:3]
	s_nop 0
	global_load_lds_dwordx4 v[134:135], off
	s_add_i32 m0, m0, 0x1000
	v_lshl_add_u64 v[132:133], v[132:133], 0, s[12:13]
	s_nop 0
	global_load_lds_dwordx4 v[142:143], off
	v_lshl_add_u64 v[134:135], v[134:135], 0, s[4:5]
	s_nop 0
	v_mov_b32_e32 v2, 0
	v_mov_b32_e32 v3, 0
	v_mov_b32_e32 v4, 0
	v_mov_b32_e32 v5, 0
	v_mov_b32_e32 v6, 0
	v_mov_b32_e32 v7, 0
	v_mov_b32_e32 v8, 0
	v_mov_b32_e32 v9, 0
	v_mov_b32_e32 v10, 0
	v_mov_b32_e32 v11, 0
	v_mov_b32_e32 v12, 0
	v_mov_b32_e32 v13, 0
	v_mov_b32_e32 v14, 0
;     ...
;   f32x4 acc[4][8];
; #pragma unroll
;   for (int i = 0; i < 4; i++)
; #pragma unroll
;     for (int j = 0; j < 8; j++) acc[i][j] = (f32x4){0.f, 0.f, 0.f, 0.f};
;     ...
;   __syncthreads();
;   G2_STAGE(0); G2_STAGE(1);
;   const int fsw = (0x78 >> (((r16 >> 2) & 3) * 2)) & 3;
;   const int aoff = (wm * 128 + r16) * 64 + ((quad ^ fsw) << 4);
;   const int boff = 16384 + (wn * 64 + r16) * 64 + ((quad ^ fsw) << 4);
;   for (int kt = 0; kt < nk; kt++) {
;     if (kt + 1 < nk) asm volatile("s_waitcnt vmcnt(6)" ::: "memory");
;     else asm volatile("s_waitcnt vmcnt(0)" ::: "memory");
;     __builtin_amdgcn_s_barrier();
;     asm volatile("" ::: "memory");
;     if (kt + 2 < nk) G2_STAGE(kt + 2);
;     const char* cS = smem + (kt % 3) * 24576;
;     bf16x8 xa[8], wb[4];
; #pragma unroll
;     for (int f = 0; f < 8; f++) xa[f] = *(const bf16x8*)(cS + aoff + f * 1024);
; #pragma unroll
;     for (int f = 0; f < 4; f++) wb[f] = *(const bf16x8*)(cS + boff + f * 1024);
; #pragma unroll
;     for (int nf = 0; nf < 4; nf++)
; #pragma unroll
;       for (int mf = 0; mf < 8; mf++)
;         acc[nf][mf] = __builtin_amdgcn_mfma_f32_16x16x32_bf16(wb[nf], xa[mf], acc[nf][mf], 0, 0, 0);
	v_mov_b32_e32 v15, 0
	v_mov_b32_e32 v16, 0
	v_mov_b32_e32 v17, 0
	v_mov_b32_e32 v18, 0
	v_mov_b32_e32 v19, 0
	v_mov_b32_e32 v20, 0
	v_mov_b32_e32 v21, 0
	v_mov_b32_e32 v22, 0
	v_mov_b32_e32 v23, 0
	v_mov_b32_e32 v24, 0
	v_mov_b32_e32 v25, 0
	v_mov_b32_e32 v26, 0
	v_mov_b32_e32 v27, 0
	v_mov_b32_e32 v28, 0
	v_mov_b32_e32 v29, 0
	v_mov_b32_e32 v30, 0
	v_mov_b32_e32 v31, 0
	v_mov_b32_e32 v32, 0
	v_mov_b32_e32 v33, 0
	v_mov_b32_e32 v34, 0
	v_mov_b32_e32 v35, 0
	v_mov_b32_e32 v36, 0
	v_mov_b32_e32 v37, 0
	v_mov_b32_e32 v38, 0
	v_mov_b32_e32 v39, 0
	v_mov_b32_e32 v40, 0
	v_mov_b32_e32 v41, 0
	v_mov_b32_e32 v42, 0
	v_mov_b32_e32 v43, 0
	v_mov_b32_e32 v44, 0
	v_mov_b32_e32 v45, 0
	v_mov_b32_e32 v46, 0
	v_mov_b32_e32 v47, 0
	v_mov_b32_e32 v48, 0
	v_mov_b32_e32 v49, 0
	v_mov_b32_e32 v50, 0
	v_mov_b32_e32 v51, 0
	v_mov_b32_e32 v52, 0
	v_mov_b32_e32 v53, 0
	v_mov_b32_e32 v54, 0
	v_mov_b32_e32 v55, 0
	v_mov_b32_e32 v56, 0
	v_mov_b32_e32 v57, 0
	v_mov_b32_e32 v58, 0
	v_mov_b32_e32 v59, 0
	v_mov_b32_e32 v60, 0
	v_mov_b32_e32 v61, 0
	v_mov_b32_e32 v62, 0
	v_mov_b32_e32 v63, 0
	v_mov_b32_e32 v64, 0
	v_mov_b32_e32 v65, 0
	v_mov_b32_e32 v66, 0
	v_mov_b32_e32 v67, 0
	v_mov_b32_e32 v68, 0
	v_mov_b32_e32 v69, 0
	v_mov_b32_e32 v70, 0
	v_mov_b32_e32 v71, 0
	v_mov_b32_e32 v72, 0
	v_mov_b32_e32 v73, 0
	v_mov_b32_e32 v74, 0
	v_mov_b32_e32 v75, 0
	v_mov_b32_e32 v76, 0
	v_mov_b32_e32 v77, 0
	v_mov_b32_e32 v78, 0
	v_mov_b32_e32 v79, 0
	v_mov_b32_e32 v80, 0
	v_mov_b32_e32 v81, 0
	v_mov_b32_e32 v82, 0
	v_mov_b32_e32 v83, 0
	v_mov_b32_e32 v84, 0
	v_mov_b32_e32 v85, 0
	v_mov_b32_e32 v86, 0
	v_mov_b32_e32 v87, 0
	v_mov_b32_e32 v88, 0
	v_mov_b32_e32 v89, 0
	v_mov_b32_e32 v90, 0
	v_mov_b32_e32 v91, 0
	v_mov_b32_e32 v92, 0
	v_mov_b32_e32 v93, 0
	v_mov_b32_e32 v94, 0
	v_mov_b32_e32 v95, 0
	v_mov_b32_e32 v96, 0
	v_mov_b32_e32 v97, 0
	v_mov_b32_e32 v98, 0
	v_mov_b32_e32 v99, 0
	v_mov_b32_e32 v100, 0
	v_mov_b32_e32 v101, 0
	v_mov_b32_e32 v102, 0
	v_mov_b32_e32 v103, 0
	v_mov_b32_e32 v104, 0
	v_mov_b32_e32 v105, 0
	v_mov_b32_e32 v106, 0
	v_mov_b32_e32 v107, 0
	v_mov_b32_e32 v108, 0
	v_mov_b32_e32 v109, 0
	v_mov_b32_e32 v110, 0
	v_mov_b32_e32 v111, 0
	v_mov_b32_e32 v112, 0
	v_mov_b32_e32 v113, 0
	v_mov_b32_e32 v114, 0
	v_mov_b32_e32 v115, 0
	v_mov_b32_e32 v116, 0
	v_mov_b32_e32 v117, 0
	v_mov_b32_e32 v118, 0
	v_mov_b32_e32 v119, 0
	v_mov_b32_e32 v120, 0
	v_mov_b32_e32 v121, 0
	v_mov_b32_e32 v122, 0
	v_mov_b32_e32 v123, 0
	v_mov_b32_e32 v124, 0
	v_mov_b32_e32 v125, 0
	v_mov_b32_e32 v126, 0
	v_mov_b32_e32 v127, 0
	v_mov_b32_e32 v128, 0
	v_mov_b32_e32 v129, 0
	s_setprio 0
	s_waitcnt vmcnt(12)
	s_barrier
	ds_read_b128 v[146:149], v136 offset:0
	ds_read_b128 v[152:155], v136 offset:1024
	ds_read_b128 v[156:159], v136 offset:2048
	ds_read_b128 v[162:165], v136 offset:3072
	ds_read_b128 v[166:169], v136 offset:4096
	ds_read_b128 v[170:173], v136 offset:5120
	ds_read_b128 v[176:179], v136 offset:6144
	ds_read_b128 v[180:183], v136 offset:7168
	ds_read_b128 v[184:187], v137 offset:16384
	ds_read_b128 v[188:191], v137 offset:17408
	ds_read_b128 v[192:195], v137 offset:18432
	ds_read_b128 v[196:199], v137 offset:19456
	s_movk_i32 s1, 0x6000
	s_mov_b32 s14, 0
	.p2align 3
	s_waitcnt vmcnt(6) lgkmcnt(0)
	s_barrier
	s_setprio 2
	v_add_u32_e32 v144, s1, v136
	v_mfma_f32_16x16x32_bf16 v[126:129], v[184:187], v[146:149], v[126:129]
	ds_read_b128 v[200:203], v144 offset:0
	v_mfma_f32_16x16x32_bf16 v[122:125], v[184:187], v[152:155], v[122:125]
	ds_read_b128 v[204:207], v144 offset:1024
	v_mfma_f32_16x16x32_bf16 v[118:121], v[184:187], v[156:159], v[118:121]
	ds_read_b128 v[208:211], v144 offset:2048
	v_mfma_f32_16x16x32_bf16 v[114:117], v[184:187], v[162:165], v[114:117]
	ds_read_b128 v[212:215], v144 offset:3072
	v_mfma_f32_16x16x32_bf16 v[110:113], v[184:187], v[166:169], v[110:113]
	ds_read_b128 v[216:219], v144 offset:4096
	v_mfma_f32_16x16x32_bf16 v[106:109], v[184:187], v[170:173], v[106:109]
	ds_read_b128 v[220:223], v144 offset:5120
	v_mfma_f32_16x16x32_bf16 v[102:105], v[184:187], v[176:179], v[102:105]
	ds_read_b128 v[224:227], v144 offset:6144
	v_mfma_f32_16x16x32_bf16 v[98:101], v[184:187], v[180:183], v[98:101]
	ds_read_b128 v[228:231], v144 offset:7168
	v_mfma_f32_16x16x32_bf16 v[94:97], v[188:191], v[146:149], v[94:97]
	v_add_u32_e64 v144, s1, v137
	v_mfma_f32_16x16x32_bf16 v[90:93], v[188:191], v[152:155], v[90:93]
	v_mfma_f32_16x16x32_bf16 v[86:89], v[188:191], v[156:159], v[86:89]
	ds_read_b128 v[232:235], v144 offset:16384
	v_mfma_f32_16x16x32_bf16 v[82:85], v[188:191], v[162:165], v[82:85]
	ds_read_b128 v[236:239], v144 offset:17408
	v_mfma_f32_16x16x32_bf16 v[78:81], v[188:191], v[166:169], v[78:81]
	ds_read_b128 v[240:243], v144 offset:18432
	v_mfma_f32_16x16x32_bf16 v[74:77], v[188:191], v[170:173], v[74:77]
	ds_read_b128 v[244:247], v144 offset:19456
	v_mfma_f32_16x16x32_bf16 v[70:73], v[188:191], v[176:179], v[70:73]
	s_add_i32 s15, s43, s14
	s_mov_b32 m0, s15
	v_lshl_add_u64 v[142:143], v[132:133], 0, s[2:3]
	v_mfma_f32_16x16x32_bf16 v[66:69], v[188:191], v[180:183], v[66:69]
	global_load_lds_dwordx4 v[132:133], off
	s_add_i32 m0, m0, 0x1000
	v_mfma_f32_16x16x32_bf16 v[62:65], v[192:195], v[146:149], v[62:65]
	v_mfma_f32_16x16x32_bf16 v[58:61], v[192:195], v[152:155], v[58:61]
	v_mfma_f32_16x16x32_bf16 v[54:57], v[192:195], v[156:159], v[54:57]
	global_load_lds_dwordx4 v[142:143], off
	v_lshl_add_u64 v[142:143], v[142:143], 0, s[2:3]
	s_add_i32 m0, m0, 0x1000
	v_mfma_f32_16x16x32_bf16 v[50:53], v[192:195], v[162:165], v[50:53]
	v_mfma_f32_16x16x32_bf16 v[46:49], v[192:195], v[166:169], v[46:49]
	v_mfma_f32_16x16x32_bf16 v[42:45], v[192:195], v[170:173], v[42:45]
	global_load_lds_dwordx4 v[142:143], off
	v_lshl_add_u64 v[142:143], v[142:143], 0, s[2:3]
	s_add_i32 m0, m0, 0x1000
	v_mfma_f32_16x16x32_bf16 v[38:41], v[192:195], v[176:179], v[38:41]
	v_mfma_f32_16x16x32_bf16 v[34:37], v[192:195], v[180:183], v[34:37]
	s_setprio 0
	s_nop 0
	v_mfma_f32_16x16x32_bf16 v[30:33], v[196:199], v[146:149], v[30:33]
	global_load_lds_dwordx4 v[142:143], off
	s_add_i32 m0, m0, 0x1000
	v_lshl_add_u64 v[142:143], v[134:135], 0, s[2:3]
	v_mfma_f32_16x16x32_bf16 v[26:29], v[196:199], v[152:155], v[26:29]
	v_mfma_f32_16x16x32_bf16 v[22:25], v[196:199], v[156:159], v[22:25]
	v_mfma_f32_16x16x32_bf16 v[18:21], v[196:199], v[162:165], v[18:21]
	global_load_lds_dwordx4 v[134:135], off
	s_add_i32 m0, m0, 0x1000
	v_lshl_add_u64 v[132:133], v[132:133], 0, s[12:13]
	v_mfma_f32_16x16x32_bf16 v[14:17], v[196:199], v[166:169], v[14:17]
	v_mfma_f32_16x16x32_bf16 v[10:13], v[196:199], v[170:173], v[10:13]
	v_mfma_f32_16x16x32_bf16 v[6:9], v[196:199], v[176:179], v[6:9]
	global_load_lds_dwordx4 v[142:143], off
	v_lshl_add_u64 v[134:135], v[134:135], 0, s[4:5]
	v_mfma_f32_16x16x32_bf16 v[2:5], v[196:199], v[180:183], v[2:5]
	s_mov_b32 s14, s1
	s_nop 0
	s_add_i32 s1, s1, 0x6000
	s_cmp_eq_u32 s1, 0x12000
	s_cselect_b32 s1, 0, s1
	s_nop 0
	.p2align 3
	s_waitcnt vmcnt(6) lgkmcnt(0)
	s_barrier
;     ...
;   for (int kt = 0; kt < nk; kt++) {
;     if (kt + 1 < nk) asm volatile("s_waitcnt vmcnt(6)" ::: "memory");
;     else asm volatile("s_waitcnt vmcnt(0)" ::: "memory");
;     __builtin_amdgcn_s_barrier();
;     asm volatile("" ::: "memory");
;     if (kt + 2 < nk) G2_STAGE(kt + 2);
;     const char* cS = smem + (kt % 3) * 24576;
;     bf16x8 xa[8], wb[4];
; #pragma unroll
;     for (int f = 0; f < 8; f++) xa[f] = *(const bf16x8*)(cS + aoff + f * 1024);
; #pragma unroll
;     for (int f = 0; f < 4; f++) wb[f] = *(const bf16x8*)(cS + boff + f * 1024);
; #pragma unroll
;     for (int nf = 0; nf < 4; nf++)
; #pragma unroll
;       for (int mf = 0; mf < 8; mf++)
;         acc[nf][mf] = __builtin_amdgcn_mfma_f32_16x16x32_bf16(wb[nf], xa[mf], acc[nf][mf], 0, 0, 0);
	s_setprio 2
	v_add_u32_e32 v144, s1, v136
	v_mfma_f32_16x16x32_bf16 v[126:129], v[232:235], v[200:203], v[126:129]
	ds_read_b128 v[146:149], v144 offset:0
	v_mfma_f32_16x16x32_bf16 v[122:125], v[232:235], v[204:207], v[122:125]
	ds_read_b128 v[152:155], v144 offset:1024
	v_mfma_f32_16x16x32_bf16 v[118:121], v[232:235], v[208:211], v[118:121]
	ds_read_b128 v[156:159], v144 offset:2048
	v_mfma_f32_16x16x32_bf16 v[114:117], v[232:235], v[212:215], v[114:117]
	ds_read_b128 v[162:165], v144 offset:3072
	v_mfma_f32_16x16x32_bf16 v[110:113], v[232:235], v[216:219], v[110:113]
	ds_read_b128 v[166:169], v144 offset:4096
	v_mfma_f32_16x16x32_bf16 v[106:109], v[232:235], v[220:223], v[106:109]
	ds_read_b128 v[170:173], v144 offset:5120
	v_mfma_f32_16x16x32_bf16 v[102:105], v[232:235], v[224:227], v[102:105]
	ds_read_b128 v[176:179], v144 offset:6144
	v_mfma_f32_16x16x32_bf16 v[98:101], v[232:235], v[228:231], v[98:101]
	ds_read_b128 v[180:183], v144 offset:7168
	v_mfma_f32_16x16x32_bf16 v[94:97], v[236:239], v[200:203], v[94:97]
	v_add_u32_e64 v144, s1, v137
	v_mfma_f32_16x16x32_bf16 v[90:93], v[236:239], v[204:207], v[90:93]
	v_mfma_f32_16x16x32_bf16 v[86:89], v[236:239], v[208:211], v[86:89]
	ds_read_b128 v[184:187], v144 offset:16384
	v_mfma_f32_16x16x32_bf16 v[82:85], v[236:239], v[212:215], v[82:85]
	ds_read_b128 v[188:191], v144 offset:17408
	v_mfma_f32_16x16x32_bf16 v[78:81], v[236:239], v[216:219], v[78:81]
	ds_read_b128 v[192:195], v144 offset:18432
	v_mfma_f32_16x16x32_bf16 v[74:77], v[236:239], v[220:223], v[74:77]
	ds_read_b128 v[196:199], v144 offset:19456
	v_mfma_f32_16x16x32_bf16 v[70:73], v[236:239], v[224:227], v[70:73]
	v_mfma_f32_16x16x32_bf16 v[66:69], v[236:239], v[228:231], v[66:69]
	v_mfma_f32_16x16x32_bf16 v[62:65], v[240:243], v[200:203], v[62:65]
	v_mfma_f32_16x16x32_bf16 v[58:61], v[240:243], v[204:207], v[58:61]
	v_mfma_f32_16x16x32_bf16 v[54:57], v[240:243], v[208:211], v[54:57]
	v_mfma_f32_16x16x32_bf16 v[50:53], v[240:243], v[212:215], v[50:53]
	v_mfma_f32_16x16x32_bf16 v[46:49], v[240:243], v[216:219], v[46:49]
	v_mfma_f32_16x16x32_bf16 v[42:45], v[240:243], v[220:223], v[42:45]
	v_mfma_f32_16x16x32_bf16 v[38:41], v[240:243], v[224:227], v[38:41]
	v_mfma_f32_16x16x32_bf16 v[34:37], v[240:243], v[228:231], v[34:37]
	s_setprio 0
	s_nop 0
	v_mfma_f32_16x16x32_bf16 v[30:33], v[244:247], v[200:203], v[30:33]
	v_mfma_f32_16x16x32_bf16 v[26:29], v[244:247], v[204:207], v[26:29]
	v_mfma_f32_16x16x32_bf16 v[22:25], v[244:247], v[208:211], v[22:25]
	v_mfma_f32_16x16x32_bf16 v[18:21], v[244:247], v[212:215], v[18:21]
	v_mfma_f32_16x16x32_bf16 v[14:17], v[244:247], v[216:219], v[14:17]
	v_mfma_f32_16x16x32_bf16 v[10:13], v[244:247], v[220:223], v[10:13]
	v_mfma_f32_16x16x32_bf16 v[6:9], v[244:247], v[224:227], v[6:9]
	v_mfma_f32_16x16x32_bf16 v[2:5], v[244:247], v[228:231], v[2:5]
	s_mov_b32 s14, s1
	s_nop 0
	s_add_i32 s1, s1, 0x6000
	s_cmp_eq_u32 s1, 0x12000
	s_cselect_b32 s1, 0, s1
	s_nop 0
	.p2align 3
	s_waitcnt vmcnt(0) lgkmcnt(0)
	s_barrier
	s_setprio 2
	v_add_u32_e32 v144, s1, v136
	v_mfma_f32_16x16x32_bf16 v[126:129], v[184:187], v[146:149], v[126:129]
	ds_read_b128 v[200:203], v144 offset:0
	v_mfma_f32_16x16x32_bf16 v[122:125], v[184:187], v[152:155], v[122:125]
	ds_read_b128 v[204:207], v144 offset:1024
	v_mfma_f32_16x16x32_bf16 v[118:121], v[184:187], v[156:159], v[118:121]
	ds_read_b128 v[208:211], v144 offset:2048
	v_mfma_f32_16x16x32_bf16 v[114:117], v[184:187], v[162:165], v[114:117]
	ds_read_b128 v[212:215], v144 offset:3072
	v_mfma_f32_16x16x32_bf16 v[110:113], v[184:187], v[166:169], v[110:113]
	ds_read_b128 v[216:219], v144 offset:4096
	v_mfma_f32_16x16x32_bf16 v[106:109], v[184:187], v[170:173], v[106:109]
	ds_read_b128 v[220:223], v144 offset:5120
	v_mfma_f32_16x16x32_bf16 v[102:105], v[184:187], v[176:179], v[102:105]
	ds_read_b128 v[224:227], v144 offset:6144
	v_mfma_f32_16x16x32_bf16 v[98:101], v[184:187], v[180:183], v[98:101]
	ds_read_b128 v[228:231], v144 offset:7168
	v_mfma_f32_16x16x32_bf16 v[94:97], v[188:191], v[146:149], v[94:97]
	v_add_u32_e64 v144, s1, v137
	v_mfma_f32_16x16x32_bf16 v[90:93], v[188:191], v[152:155], v[90:93]
	v_mfma_f32_16x16x32_bf16 v[86:89], v[188:191], v[156:159], v[86:89]
	ds_read_b128 v[232:235], v144 offset:16384
	v_mfma_f32_16x16x32_bf16 v[82:85], v[188:191], v[162:165], v[82:85]
	ds_read_b128 v[236:239], v144 offset:17408
	v_mfma_f32_16x16x32_bf16 v[78:81], v[188:191], v[166:169], v[78:81]
	ds_read_b128 v[240:243], v144 offset:18432
	v_mfma_f32_16x16x32_bf16 v[74:77], v[188:191], v[170:173], v[74:77]
	ds_read_b128 v[244:247], v144 offset:19456
	v_mfma_f32_16x16x32_bf16 v[70:73], v[188:191], v[176:179], v[70:73]
	v_mfma_f32_16x16x32_bf16 v[66:69], v[188:191], v[180:183], v[66:69]
	v_mfma_f32_16x16x32_bf16 v[62:65], v[192:195], v[146:149], v[62:65]
	v_mfma_f32_16x16x32_bf16 v[58:61], v[192:195], v[152:155], v[58:61]
	v_mfma_f32_16x16x32_bf16 v[54:57], v[192:195], v[156:159], v[54:57]
	v_mfma_f32_16x16x32_bf16 v[50:53], v[192:195], v[162:165], v[50:53]
	v_mfma_f32_16x16x32_bf16 v[46:49], v[192:195], v[166:169], v[46:49]
	v_mfma_f32_16x16x32_bf16 v[42:45], v[192:195], v[170:173], v[42:45]
	v_mfma_f32_16x16x32_bf16 v[38:41], v[192:195], v[176:179], v[38:41]
	v_mfma_f32_16x16x32_bf16 v[34:37], v[192:195], v[180:183], v[34:37]
	s_setprio 0
	s_nop 0
	v_mfma_f32_16x16x32_bf16 v[30:33], v[196:199], v[146:149], v[30:33]
	v_mfma_f32_16x16x32_bf16 v[26:29], v[196:199], v[152:155], v[26:29]
	v_mfma_f32_16x16x32_bf16 v[22:25], v[196:199], v[156:159], v[22:25]
	v_mfma_f32_16x16x32_bf16 v[18:21], v[196:199], v[162:165], v[18:21]
	v_mfma_f32_16x16x32_bf16 v[14:17], v[196:199], v[166:169], v[14:17]
	v_mfma_f32_16x16x32_bf16 v[10:13], v[196:199], v[170:173], v[10:13]
	v_mfma_f32_16x16x32_bf16 v[6:9], v[196:199], v[176:179], v[6:9]
	v_mfma_f32_16x16x32_bf16 v[2:5], v[196:199], v[180:183], v[2:5]
	s_mov_b32 s14, s1
	s_nop 0
	s_add_i32 s1, s1, 0x6000
	s_cmp_eq_u32 s1, 0x12000
	s_cselect_b32 s1, 0, s1
	s_nop 0
	s_mov_b32 s4, 0x8000
	s_mov_b32 s5, 0
	s_mov_b32 s10, 0x10000
	s_mov_b32 s11, 0
	s_mov_b32 s41, 0x3fd744fd
	.p2align 3
	s_waitcnt lgkmcnt(0)
; DEVI float blo(unsigned u) { return __uint_as_float(u << 16); }
; DEVI float bhi(unsigned u) { return __uint_as_float(u & 0xffff0000u); }
;     ...
;     for (int nf = 0; nf < 4; nf++)
; #pragma unroll
;       for (int mf = 0; mf < 8; mf++)
;         acc[nf][mf] = __builtin_amdgcn_mfma_f32_16x16x32_bf16(wb[nf], xa[mf], acc[nf][mf], 0, 0, 0);
;     ...
; #pragma unroll
;       for (int nf = 0; nf < 4; nf++) {
;         const int col = n0 + wn * 64 + nf * 16 + quad * 4;
;         f32x4 a = acc[nf][mf];
;         if (EPI == EPI_RESID || EPI == EPI_RESID_ATOMIC) {
;           f32x4 x = a;
;           if (EPI == EPI_RESID || kpart == 0) {
;             const u32x2 xr = *(const u32x2*)((const u16*)(p.ws + WS_XB) + (size_t)row * 1024 + col);
;             x[0] += ALPHA * blo(xr[0]); x[1] += ALPHA * bhi(xr[0]); x[2] += ALPHA * blo(xr[1]); x[3] += ALPHA * bhi(xr[1]);
;           }
;           if (EPI == EPI_RESID) *(f32x4*)((float*)(p.ws + WS_XF) + (size_t)row * 1024 + col) = x;
;           else *(f32x4*)((float*)(p.ws + WS_SLAB) + ((size_t)kpart * 512 + (row - T_P)) * 1024 + col) = x;
	s_nop 0
	v_mfma_f32_16x16x32_bf16 v[126:129], v[232:235], v[200:203], v[126:129]
	v_mfma_f32_16x16x32_bf16 v[122:125], v[232:235], v[204:207], v[122:125]
	v_mfma_f32_16x16x32_bf16 v[118:121], v[232:235], v[208:211], v[118:121]
	v_mfma_f32_16x16x32_bf16 v[114:117], v[232:235], v[212:215], v[114:117]
	v_mfma_f32_16x16x32_bf16 v[110:113], v[232:235], v[216:219], v[110:113]
	v_mfma_f32_16x16x32_bf16 v[106:109], v[232:235], v[220:223], v[106:109]
	v_mfma_f32_16x16x32_bf16 v[102:105], v[232:235], v[224:227], v[102:105]
	v_mfma_f32_16x16x32_bf16 v[98:101], v[232:235], v[228:231], v[98:101]
	v_mfma_f32_16x16x32_bf16 v[94:97], v[236:239], v[200:203], v[94:97]
	v_mfma_f32_16x16x32_bf16 v[90:93], v[236:239], v[204:207], v[90:93]
	v_mfma_f32_16x16x32_bf16 v[86:89], v[236:239], v[208:211], v[86:89]
	v_mfma_f32_16x16x32_bf16 v[82:85], v[236:239], v[212:215], v[82:85]
	v_mfma_f32_16x16x32_bf16 v[78:81], v[236:239], v[216:219], v[78:81]
	v_mfma_f32_16x16x32_bf16 v[74:77], v[236:239], v[220:223], v[74:77]
	v_mfma_f32_16x16x32_bf16 v[70:73], v[236:239], v[224:227], v[70:73]
	v_mfma_f32_16x16x32_bf16 v[66:69], v[236:239], v[228:231], v[66:69]
	v_mfma_f32_16x16x32_bf16 v[62:65], v[240:243], v[200:203], v[62:65]
	v_mfma_f32_16x16x32_bf16 v[58:61], v[240:243], v[204:207], v[58:61]
	v_mfma_f32_16x16x32_bf16 v[54:57], v[240:243], v[208:211], v[54:57]
	v_mfma_f32_16x16x32_bf16 v[50:53], v[240:243], v[212:215], v[50:53]
	v_mfma_f32_16x16x32_bf16 v[46:49], v[240:243], v[216:219], v[46:49]
	v_mfma_f32_16x16x32_bf16 v[42:45], v[240:243], v[220:223], v[42:45]
	v_mfma_f32_16x16x32_bf16 v[38:41], v[240:243], v[224:227], v[38:41]
	v_mfma_f32_16x16x32_bf16 v[34:37], v[240:243], v[228:231], v[34:37]
	v_mfma_f32_16x16x32_bf16 v[30:33], v[244:247], v[200:203], v[30:33]
	v_mfma_f32_16x16x32_bf16 v[26:29], v[244:247], v[204:207], v[26:29]
	v_mfma_f32_16x16x32_bf16 v[22:25], v[244:247], v[208:211], v[22:25]
	v_mfma_f32_16x16x32_bf16 v[18:21], v[244:247], v[212:215], v[18:21]
	v_mfma_f32_16x16x32_bf16 v[14:17], v[244:247], v[216:219], v[14:17]
	v_mfma_f32_16x16x32_bf16 v[10:13], v[244:247], v[220:223], v[10:13]
	v_mfma_f32_16x16x32_bf16 v[6:9], v[244:247], v[224:227], v[6:9]
	v_mfma_f32_16x16x32_bf16 v[2:5], v[244:247], v[228:231], v[2:5]
	s_mov_b32 m0, s40
	s_cmp_eq_u32 s98, 0
	s_cbranch_scc1 .Lta4_first
	s_nop 7
	global_store_dwordx4 v[140:141], v[126:129], off offset:0
	global_store_dwordx4 v[140:141], v[94:97], off offset:64
	global_store_dwordx4 v[140:141], v[62:65], off offset:128
	global_store_dwordx4 v[140:141], v[30:33], off offset:192
	v_lshl_add_u64 v[140:141], v[140:141], 0, s[10:11]
	global_store_dwordx4 v[140:141], v[122:125], off offset:0
	global_store_dwordx4 v[140:141], v[90:93], off offset:64
	global_store_dwordx4 v[140:141], v[58:61], off offset:128
	global_store_dwordx4 v[140:141], v[26:29], off offset:192
	v_lshl_add_u64 v[140:141], v[140:141], 0, s[10:11]
	global_store_dwordx4 v[140:141], v[118:121], off offset:0
	global_store_dwordx4 v[140:141], v[86:89], off offset:64
	global_store_dwordx4 v[140:141], v[54:57], off offset:128
	global_store_dwordx4 v[140:141], v[22:25], off offset:192
	v_lshl_add_u64 v[140:141], v[140:141], 0, s[10:11]
	global_store_dwordx4 v[140:141], v[114:117], off offset:0
	global_store_dwordx4 v[140:141], v[82:85], off offset:64
	global_store_dwordx4 v[140:141], v[50:53], off offset:128
	global_store_dwordx4 v[140:141], v[18:21], off offset:192
	v_lshl_add_u64 v[140:141], v[140:141], 0, s[10:11]
	global_store_dwordx4 v[140:141], v[110:113], off offset:0
	global_store_dwordx4 v[140:141], v[78:81], off offset:64
	global_store_dwordx4 v[140:141], v[46:49], off offset:128
	global_store_dwordx4 v[140:141], v[14:17], off offset:192
	v_lshl_add_u64 v[140:141], v[140:141], 0, s[10:11]
	global_store_dwordx4 v[140:141], v[106:109], off offset:0
	global_store_dwordx4 v[140:141], v[74:77], off offset:64
	global_store_dwordx4 v[140:141], v[42:45], off offset:128
	global_store_dwordx4 v[140:141], v[10:13], off offset:192
	v_lshl_add_u64 v[140:141], v[140:141], 0, s[10:11]
	global_store_dwordx4 v[140:141], v[102:105], off offset:0
	global_store_dwordx4 v[140:141], v[70:73], off offset:64
	global_store_dwordx4 v[140:141], v[38:41], off offset:128
	global_store_dwordx4 v[140:141], v[6:9], off offset:192
	v_lshl_add_u64 v[140:141], v[140:141], 0, s[10:11]
	global_store_dwordx4 v[140:141], v[98:101], off offset:0
	global_store_dwordx4 v[140:141], v[66:69], off offset:64
	global_store_dwordx4 v[140:141], v[34:37], off offset:128
	global_store_dwordx4 v[140:141], v[2:5], off offset:192
	v_readlane_b32 s0, v250, 7
	s_cmpk_lg_u32 s0, 0x200
	s_cbranch_scc1 .Lta4_ar1
	s_mov_b32 s0, 1
	v_writelane_b32 v255, s0, 41
	v_readlane_b32 s1, v250, 0
	s_lshr_b32 s14, s1, 3
	s_and_b32 s1, s1, 7
	s_lshl_b32 s1, s1, 6
	s_add_i32 s1, s1, s14
	s_sub_i32 s39, s1, 0x200
